# K-loop MFMA order: boustrophedon over (B-pair, A-pair), same-accumulator k0/k1 back to back, chain-aware
# speedup vs baseline: 1.0152x; 1.0001x over previous
.LBB0_411:
	s_add_u32 s16, s14, 0xfffc0080
	s_addc_u32 s17, s15, -1
	s_add_i32 s51, 0, 0x10000
	s_cmp_eq_u32 s50, 12
	s_cselect_b32 s21, s9, s17
	s_cselect_b32 s20, s46, s16
	s_cselect_b32 s17, s5, s49
	s_cselect_b32 s16, s47, s48
	s_add_i32 s54, 0, 0x14000
	v_add_u32_e32 v154, s51, v181
	v_add_u32_e32 v162, s54, v181
	ds_read_b128 v[130:133], v154
	ds_read_b128 v[134:137], v154 offset:1024
	ds_read_b128 v[150:153], v154 offset:2048
	ds_read_b128 v[154:157], v154 offset:3072
	ds_read_b128 v[158:161], v162
	ds_read_b128 v[174:177], v162 offset:1024
	ds_read_b128 v[186:189], v162 offset:2048
	ds_read_b128 v[190:193], v162 offset:3072
	s_add_i32 m0, s26, 0xc000
	ds_read_b128 v[194:197], v184
	ds_read_b128 v[198:201], v184 offset:1024
	ds_read_b128 v[202:205], v184 offset:2048
	ds_read_b128 v[206:209], v184 offset:3072
	ds_read_b128 v[224:227], v184 offset:4096
	ds_read_b128 v[228:231], v184 offset:5120
	ds_read_b128 v[232:235], v184 offset:6144
	ds_read_b128 v[236:239], v184 offset:7168
	global_load_lds_dwordx4 v146, s[14:15]
	s_add_i32 m0, s26, 0xe000
	s_nop 0
	global_load_lds_dwordx4 v148, s[14:15]
	s_waitcnt vmcnt(8)
	s_waitcnt lgkmcnt(0)
	s_barrier
	s_setprio 1
	s_waitcnt lgkmcnt(0)
	v_mfma_i32_16x16x64_i8 v[126:129], v[130:133], v[194:197], v[126:129]
	v_mfma_i32_16x16x64_i8 v[126:129], v[134:137], v[198:201], v[126:129]
	v_mfma_i32_16x16x64_i8 v[110:113], v[130:133], v[202:205], v[110:113]
	v_mfma_i32_16x16x64_i8 v[110:113], v[134:137], v[206:209], v[110:113]
	v_mfma_i32_16x16x64_i8 v[94:97], v[130:133], v[224:227], v[94:97]
	v_mfma_i32_16x16x64_i8 v[94:97], v[134:137], v[228:231], v[94:97]
	v_mfma_i32_16x16x64_i8 v[78:81], v[130:133], v[232:235], v[78:81]
	v_mfma_i32_16x16x64_i8 v[78:81], v[134:137], v[236:239], v[78:81]
	v_mfma_i32_16x16x64_i8 v[70:73], v[150:153], v[232:235], v[70:73]
	v_mfma_i32_16x16x64_i8 v[70:73], v[154:157], v[236:239], v[70:73]
	v_mfma_i32_16x16x64_i8 v[86:89], v[150:153], v[224:227], v[86:89]
	v_mfma_i32_16x16x64_i8 v[86:89], v[154:157], v[228:231], v[86:89]
	v_mfma_i32_16x16x64_i8 v[102:105], v[150:153], v[202:205], v[102:105]
	v_mfma_i32_16x16x64_i8 v[102:105], v[154:157], v[206:209], v[102:105]
	v_mfma_i32_16x16x64_i8 v[122:125], v[150:153], v[194:197], v[122:125]
	v_mfma_i32_16x16x64_i8 v[122:125], v[154:157], v[198:201], v[122:125]
	v_mfma_i32_16x16x64_i8 v[118:121], v[158:161], v[194:197], v[118:121]
	v_mfma_i32_16x16x64_i8 v[118:121], v[174:177], v[198:201], v[118:121]
	v_mfma_i32_16x16x64_i8 v[106:109], v[158:161], v[202:205], v[106:109]
	v_mfma_i32_16x16x64_i8 v[106:109], v[174:177], v[206:209], v[106:109]
	v_mfma_i32_16x16x64_i8 v[90:93], v[158:161], v[224:227], v[90:93]
	v_mfma_i32_16x16x64_i8 v[90:93], v[174:177], v[228:231], v[90:93]
	v_mfma_i32_16x16x64_i8 v[74:77], v[158:161], v[232:235], v[74:77]
	v_mfma_i32_16x16x64_i8 v[74:77], v[174:177], v[236:239], v[74:77]
	v_mfma_i32_16x16x64_i8 v[66:69], v[186:189], v[232:235], v[66:69]
	v_mfma_i32_16x16x64_i8 v[66:69], v[190:193], v[236:239], v[66:69]
	v_mfma_i32_16x16x64_i8 v[82:85], v[186:189], v[224:227], v[82:85]
	v_mfma_i32_16x16x64_i8 v[82:85], v[190:193], v[228:231], v[82:85]
	v_mfma_i32_16x16x64_i8 v[98:101], v[186:189], v[202:205], v[98:101]
	v_mfma_i32_16x16x64_i8 v[98:101], v[190:193], v[206:209], v[98:101]
	v_mfma_i32_16x16x64_i8 v[114:117], v[186:189], v[194:197], v[114:117]
	v_mfma_i32_16x16x64_i8 v[114:117], v[190:193], v[198:201], v[114:117]
	s_setprio 0
	s_barrier
	s_add_i32 s51, s51, s33
	v_lshl_add_u64 v[162:163], s[16:17], 0, v[0:1]
	s_mov_b32 m0, s51
	ds_read_b128 v[194:197], v184 offset:16384
	ds_read_b128 v[198:201], v184 offset:17408
	ds_read_b128 v[202:205], v184 offset:18432
	ds_read_b128 v[206:209], v184 offset:19456
	ds_read_b128 v[224:227], v184 offset:20480
	ds_read_b128 v[228:231], v184 offset:21504
	ds_read_b128 v[232:235], v184 offset:22528
	ds_read_b128 v[236:239], v184 offset:23552
	global_load_lds_dwordx4 v[162:163], off
	s_add_i32 m0, s51, 0x2000
	s_add_u32 s52, s16, 0x40000
	v_lshl_add_u64 v[164:165], s[16:17], 0, v[138:139]
	s_addc_u32 s53, s17, 0
	s_add_i32 s51, s54, s33
	global_load_lds_dwordx4 v[164:165], off
	s_mov_b32 m0, s51
	v_lshl_add_u64 v[168:169], s[20:21], 0, v[140:141]
	global_load_lds_dwordx4 v0, s[52:53]
	s_add_i32 m0, s51, 0x2000
	s_nop 0
	global_load_lds_dwordx4 v138, s[52:53]
	v_lshl_add_u64 v[166:167], s[20:21], 0, v[142:143]
	s_mov_b32 m0, s26
	s_nop 0
	global_load_lds_dwordx4 v[166:167], off
	s_mov_b32 m0, s27
	s_nop 0
	global_load_lds_dwordx4 v[168:169], off
	s_waitcnt vmcnt(8)
	s_waitcnt lgkmcnt(0)
	s_barrier
	s_setprio 1
	s_waitcnt lgkmcnt(0)
	v_mfma_i32_16x16x64_i8 v[62:65], v[130:133], v[194:197], v[62:65]
	v_mfma_i32_16x16x64_i8 v[62:65], v[134:137], v[198:201], v[62:65]
	v_mfma_i32_16x16x64_i8 v[46:49], v[130:133], v[202:205], v[46:49]
	v_mfma_i32_16x16x64_i8 v[46:49], v[134:137], v[206:209], v[46:49]
	v_mfma_i32_16x16x64_i8 v[30:33], v[130:133], v[224:227], v[30:33]
	v_mfma_i32_16x16x64_i8 v[30:33], v[134:137], v[228:231], v[30:33]
	v_mfma_i32_16x16x64_i8 v[14:17], v[130:133], v[232:235], v[14:17]
	v_mfma_i32_16x16x64_i8 v[14:17], v[134:137], v[236:239], v[14:17]
	v_mfma_i32_16x16x64_i8 v[6:9], v[150:153], v[232:235], v[6:9]
	v_mfma_i32_16x16x64_i8 v[6:9], v[154:157], v[236:239], v[6:9]
	v_mfma_i32_16x16x64_i8 v[22:25], v[150:153], v[224:227], v[22:25]
	v_mfma_i32_16x16x64_i8 v[22:25], v[154:157], v[228:231], v[22:25]
	v_mfma_i32_16x16x64_i8 v[38:41], v[150:153], v[202:205], v[38:41]
	v_mfma_i32_16x16x64_i8 v[38:41], v[154:157], v[206:209], v[38:41]
	v_mfma_i32_16x16x64_i8 v[54:57], v[150:153], v[194:197], v[54:57]
	v_mfma_i32_16x16x64_i8 v[54:57], v[154:157], v[198:201], v[54:57]
	v_mfma_i32_16x16x64_i8 v[58:61], v[158:161], v[194:197], v[58:61]
	v_mfma_i32_16x16x64_i8 v[58:61], v[174:177], v[198:201], v[58:61]
	v_mfma_i32_16x16x64_i8 v[42:45], v[158:161], v[202:205], v[42:45]
	v_mfma_i32_16x16x64_i8 v[42:45], v[174:177], v[206:209], v[42:45]
	v_mfma_i32_16x16x64_i8 v[26:29], v[158:161], v[224:227], v[26:29]
	v_mfma_i32_16x16x64_i8 v[26:29], v[174:177], v[228:231], v[26:29]
	v_mfma_i32_16x16x64_i8 v[10:13], v[158:161], v[232:235], v[10:13]
	v_mfma_i32_16x16x64_i8 v[10:13], v[174:177], v[236:239], v[10:13]
	v_mfma_i32_16x16x64_i8 v[2:5], v[186:189], v[232:235], v[2:5]
	v_mfma_i32_16x16x64_i8 v[2:5], v[190:193], v[236:239], v[2:5]
	v_mfma_i32_16x16x64_i8 v[18:21], v[186:189], v[224:227], v[18:21]
	v_mfma_i32_16x16x64_i8 v[18:21], v[190:193], v[228:231], v[18:21]
	v_mfma_i32_16x16x64_i8 v[34:37], v[186:189], v[202:205], v[34:37]
	v_mfma_i32_16x16x64_i8 v[34:37], v[190:193], v[206:209], v[34:37]
	v_mfma_i32_16x16x64_i8 v[50:53], v[186:189], v[194:197], v[50:53]
	v_mfma_i32_16x16x64_i8 v[50:53], v[190:193], v[198:201], v[50:53]
	s_setprio 0
	s_barrier
	s_add_i32 s51, 0, 0x18000
	s_add_i32 s52, 0, 0x1c000
	v_add_u32_e32 v154, s51, v181
	v_add_u32_e32 v170, s52, v181
	ds_read_b128 v[130:133], v154
	ds_read_b128 v[134:137], v154 offset:1024
	ds_read_b128 v[150:153], v154 offset:2048
	ds_read_b128 v[154:157], v154 offset:3072
	ds_read_b128 v[158:161], v170
	ds_read_b128 v[174:177], v170 offset:1024
	ds_read_b128 v[186:189], v170 offset:2048
	ds_read_b128 v[190:193], v170 offset:3072
	s_add_u32 s20, s20, 0x40000
	s_addc_u32 s21, s21, 0
	s_mov_b32 m0, s28
	ds_read_b128 v[194:197], v184 offset:32768
	ds_read_b128 v[198:201], v184 offset:33792
	ds_read_b128 v[202:205], v184 offset:34816
	ds_read_b128 v[206:209], v184 offset:35840
	ds_read_b128 v[224:227], v184 offset:36864
	ds_read_b128 v[228:231], v184 offset:37888
	ds_read_b128 v[232:235], v184 offset:38912
	ds_read_b128 v[236:239], v184 offset:39936
	global_load_lds_dwordx4 v142, s[20:21]
	s_mov_b32 m0, s29
	s_nop 0
	global_load_lds_dwordx4 v140, s[20:21]
	s_waitcnt vmcnt(8)
	s_waitcnt lgkmcnt(0)
	s_barrier
	s_setprio 1
	s_waitcnt lgkmcnt(0)
	v_mfma_i32_16x16x64_i8 v[126:129], v[130:133], v[194:197], v[126:129]
	v_mfma_i32_16x16x64_i8 v[126:129], v[134:137], v[198:201], v[126:129]
	v_mfma_i32_16x16x64_i8 v[110:113], v[130:133], v[202:205], v[110:113]
	v_mfma_i32_16x16x64_i8 v[110:113], v[134:137], v[206:209], v[110:113]
	v_mfma_i32_16x16x64_i8 v[94:97], v[130:133], v[224:227], v[94:97]
	v_mfma_i32_16x16x64_i8 v[94:97], v[134:137], v[228:231], v[94:97]
	v_mfma_i32_16x16x64_i8 v[78:81], v[130:133], v[232:235], v[78:81]
	v_mfma_i32_16x16x64_i8 v[78:81], v[134:137], v[236:239], v[78:81]
	v_mfma_i32_16x16x64_i8 v[70:73], v[150:153], v[232:235], v[70:73]
	v_mfma_i32_16x16x64_i8 v[70:73], v[154:157], v[236:239], v[70:73]
	v_mfma_i32_16x16x64_i8 v[86:89], v[150:153], v[224:227], v[86:89]
	v_mfma_i32_16x16x64_i8 v[86:89], v[154:157], v[228:231], v[86:89]
	v_mfma_i32_16x16x64_i8 v[102:105], v[150:153], v[202:205], v[102:105]
	v_mfma_i32_16x16x64_i8 v[102:105], v[154:157], v[206:209], v[102:105]
	v_mfma_i32_16x16x64_i8 v[122:125], v[150:153], v[194:197], v[122:125]
	v_mfma_i32_16x16x64_i8 v[122:125], v[154:157], v[198:201], v[122:125]
	v_mfma_i32_16x16x64_i8 v[118:121], v[158:161], v[194:197], v[118:121]
	v_mfma_i32_16x16x64_i8 v[118:121], v[174:177], v[198:201], v[118:121]
	v_mfma_i32_16x16x64_i8 v[106:109], v[158:161], v[202:205], v[106:109]
	v_mfma_i32_16x16x64_i8 v[106:109], v[174:177], v[206:209], v[106:109]
	v_mfma_i32_16x16x64_i8 v[90:93], v[158:161], v[224:227], v[90:93]
	v_mfma_i32_16x16x64_i8 v[90:93], v[174:177], v[228:231], v[90:93]
	v_mfma_i32_16x16x64_i8 v[74:77], v[158:161], v[232:235], v[74:77]
	v_mfma_i32_16x16x64_i8 v[74:77], v[174:177], v[236:239], v[74:77]
	v_mfma_i32_16x16x64_i8 v[66:69], v[186:189], v[232:235], v[66:69]
	v_mfma_i32_16x16x64_i8 v[66:69], v[190:193], v[236:239], v[66:69]
	v_mfma_i32_16x16x64_i8 v[82:85], v[186:189], v[224:227], v[82:85]
	v_mfma_i32_16x16x64_i8 v[82:85], v[190:193], v[228:231], v[82:85]
	v_mfma_i32_16x16x64_i8 v[98:101], v[186:189], v[202:205], v[98:101]
	v_mfma_i32_16x16x64_i8 v[98:101], v[190:193], v[206:209], v[98:101]
	v_mfma_i32_16x16x64_i8 v[114:117], v[186:189], v[194:197], v[114:117]
	v_mfma_i32_16x16x64_i8 v[114:117], v[190:193], v[198:201], v[114:117]
	s_setprio 0
	s_barrier
	s_add_i32 s20, s51, s33
	v_lshl_add_u64 v[162:163], v[162:163], 0, s[30:31]
	s_mov_b32 m0, s20
	ds_read_b128 v[194:197], v184 offset:49152
	ds_read_b128 v[198:201], v184 offset:50176
	ds_read_b128 v[202:205], v184 offset:51200
	ds_read_b128 v[206:209], v184 offset:52224
	ds_read_b128 v[224:227], v184 offset:53248
	ds_read_b128 v[228:231], v184 offset:54272
	ds_read_b128 v[232:235], v184 offset:55296
	ds_read_b128 v[236:239], v184 offset:56320
	global_load_lds_dwordx4 v[162:163], off
	s_add_i32 m0, s20, 0x2000
	s_add_u32 s16, s16, 0x40080
	v_lshl_add_u64 v[162:163], v[164:165], 0, s[30:31]
	s_addc_u32 s17, s17, 0
	s_add_i32 s20, s52, s33
	global_load_lds_dwordx4 v[162:163], off
	s_mov_b32 m0, s20
	s_nop 0
	global_load_lds_dwordx4 v0, s[16:17]
	s_add_i32 m0, s20, 0x2000
	s_nop 0
	global_load_lds_dwordx4 v138, s[16:17]
	v_lshl_add_u64 v[162:163], v[166:167], 0, s[30:31]
	s_mov_b32 m0, s34
	s_nop 0
	global_load_lds_dwordx4 v[162:163], off
	v_lshl_add_u64 v[162:163], v[168:169], 0, s[30:31]
	s_mov_b32 m0, s35
	s_nop 0
	global_load_lds_dwordx4 v[162:163], off
	s_waitcnt vmcnt(8)
	s_waitcnt lgkmcnt(0)
	s_barrier
	s_setprio 1
	s_waitcnt lgkmcnt(0)
	v_mfma_i32_16x16x64_i8 v[62:65], v[130:133], v[194:197], v[62:65]
	v_mfma_i32_16x16x64_i8 v[62:65], v[134:137], v[198:201], v[62:65]
	v_mfma_i32_16x16x64_i8 v[46:49], v[130:133], v[202:205], v[46:49]
	v_mfma_i32_16x16x64_i8 v[46:49], v[134:137], v[206:209], v[46:49]
	v_mfma_i32_16x16x64_i8 v[30:33], v[130:133], v[224:227], v[30:33]
	v_mfma_i32_16x16x64_i8 v[30:33], v[134:137], v[228:231], v[30:33]
	v_mfma_i32_16x16x64_i8 v[14:17], v[130:133], v[232:235], v[14:17]
	v_mfma_i32_16x16x64_i8 v[14:17], v[134:137], v[236:239], v[14:17]
	v_mfma_i32_16x16x64_i8 v[6:9], v[150:153], v[232:235], v[6:9]
	v_mfma_i32_16x16x64_i8 v[6:9], v[154:157], v[236:239], v[6:9]
	v_mfma_i32_16x16x64_i8 v[22:25], v[150:153], v[224:227], v[22:25]
	v_mfma_i32_16x16x64_i8 v[22:25], v[154:157], v[228:231], v[22:25]
	v_mfma_i32_16x16x64_i8 v[38:41], v[150:153], v[202:205], v[38:41]
	v_mfma_i32_16x16x64_i8 v[38:41], v[154:157], v[206:209], v[38:41]
	v_mfma_i32_16x16x64_i8 v[54:57], v[150:153], v[194:197], v[54:57]
	v_mfma_i32_16x16x64_i8 v[54:57], v[154:157], v[198:201], v[54:57]
	v_mfma_i32_16x16x64_i8 v[58:61], v[158:161], v[194:197], v[58:61]
	v_mfma_i32_16x16x64_i8 v[58:61], v[174:177], v[198:201], v[58:61]
	v_mfma_i32_16x16x64_i8 v[42:45], v[158:161], v[202:205], v[42:45]
	v_mfma_i32_16x16x64_i8 v[42:45], v[174:177], v[206:209], v[42:45]
	v_mfma_i32_16x16x64_i8 v[26:29], v[158:161], v[224:227], v[26:29]
	v_mfma_i32_16x16x64_i8 v[26:29], v[174:177], v[228:231], v[26:29]
	v_mfma_i32_16x16x64_i8 v[10:13], v[158:161], v[232:235], v[10:13]
	v_mfma_i32_16x16x64_i8 v[10:13], v[174:177], v[236:239], v[10:13]
	v_mfma_i32_16x16x64_i8 v[2:5], v[186:189], v[232:235], v[2:5]
	v_mfma_i32_16x16x64_i8 v[2:5], v[190:193], v[236:239], v[2:5]
	v_mfma_i32_16x16x64_i8 v[18:21], v[186:189], v[224:227], v[18:21]
	v_mfma_i32_16x16x64_i8 v[18:21], v[190:193], v[228:231], v[18:21]
	v_mfma_i32_16x16x64_i8 v[34:37], v[186:189], v[202:205], v[34:37]
	v_mfma_i32_16x16x64_i8 v[34:37], v[190:193], v[206:209], v[34:37]
	v_mfma_i32_16x16x64_i8 v[50:53], v[186:189], v[194:197], v[50:53]
	v_mfma_i32_16x16x64_i8 v[50:53], v[190:193], v[198:201], v[50:53]
	s_setprio 0
	s_barrier
	s_add_i32 s50, s50, 2
	s_add_u32 s14, s14, 0x100
	s_addc_u32 s15, s15, 0
	s_add_u32 s48, s48, 0x100
	s_addc_u32 s49, s49, 0
	s_cmp_gt_u32 s50, 13
	s_cbranch_scc0 .LBB0_411
	v_readlane_b32 s14, v253, 2
	v_readlane_b32 s15, v253, 3
	s_and_b64 vcc, exec, s[14:15]
	s_cbranch_vccz .LBB0_414
	s_barrier

.LBB0_493:
	s_add_u32 s16, s12, 0x100
	s_addc_u32 s17, s13, 0
	s_add_i32 s67, 0, 0x10000
	s_cmpk_eq_i32 s19, 0x54
	s_cselect_b32 s23, s7, s17
	s_cselect_b32 s22, s6, s16
	s_cselect_b32 s21, s11, s18
	s_cselect_b32 s20, s10, s15
	s_add_i32 s68, 0, 0x14000
	v_add_u32_e32 v142, s67, v205
	v_add_u32_e32 v162, s68, v205
	ds_read_b128 v[130:133], v142
	ds_read_b128 v[134:137], v142 offset:1024
	ds_read_b128 v[138:141], v142 offset:2048
	ds_read_b128 v[142:145], v142 offset:3072
	ds_read_b128 v[146:149], v162
	ds_read_b128 v[150:153], v162 offset:1024
	ds_read_b128 v[154:157], v162 offset:2048
	ds_read_b128 v[184:187], v162 offset:3072
	s_add_i32 m0, s28, 0xc000
	ds_read_b128 v[188:191], v230
	ds_read_b128 v[192:195], v230 offset:1024
	ds_read_b128 v[196:199], v230 offset:2048
	ds_read_b128 v[200:203], v230 offset:3072
	ds_read_b128 v[232:235], v230 offset:4096
	ds_read_b128 v[236:239], v230 offset:5120
	ds_read_b128 v[240:243], v230 offset:6144
	ds_read_b128 v[244:247], v230 offset:7168
	global_load_lds_dwordx4 v180, s[12:13]
	s_add_i32 m0, s28, 0xe000
	s_nop 0
	global_load_lds_dwordx4 v182, s[12:13]
	s_waitcnt vmcnt(8)
	s_waitcnt lgkmcnt(0)
	s_barrier
	s_setprio 1
	s_waitcnt lgkmcnt(0)
	v_mfma_f32_16x16x32_bf16 v[126:129], v[130:133], v[188:191], v[126:129]
	v_mfma_f32_16x16x32_bf16 v[126:129], v[134:137], v[192:195], v[126:129]
	v_mfma_f32_16x16x32_bf16 v[118:121], v[130:133], v[196:199], v[118:121]
	v_mfma_f32_16x16x32_bf16 v[118:121], v[134:137], v[200:203], v[118:121]
	v_mfma_f32_16x16x32_bf16 v[110:113], v[130:133], v[232:235], v[110:113]
	v_mfma_f32_16x16x32_bf16 v[110:113], v[134:137], v[236:239], v[110:113]
	v_mfma_f32_16x16x32_bf16 v[102:105], v[130:133], v[240:243], v[102:105]
	v_mfma_f32_16x16x32_bf16 v[102:105], v[134:137], v[244:247], v[102:105]
	v_mfma_f32_16x16x32_bf16 v[38:41], v[138:141], v[240:243], v[38:41]
	v_mfma_f32_16x16x32_bf16 v[38:41], v[142:145], v[244:247], v[38:41]
	v_mfma_f32_16x16x32_bf16 v[66:69], v[138:141], v[232:235], v[66:69]
	v_mfma_f32_16x16x32_bf16 v[66:69], v[142:145], v[236:239], v[66:69]
	v_mfma_f32_16x16x32_bf16 v[86:89], v[138:141], v[196:199], v[86:89]
	v_mfma_f32_16x16x32_bf16 v[86:89], v[142:145], v[200:203], v[86:89]
	v_mfma_f32_16x16x32_bf16 v[74:77], v[138:141], v[188:191], v[74:77]
	v_mfma_f32_16x16x32_bf16 v[74:77], v[142:145], v[192:195], v[74:77]
	v_mfma_f32_16x16x32_bf16 v[122:125], v[146:149], v[188:191], v[122:125]
	v_mfma_f32_16x16x32_bf16 v[122:125], v[150:153], v[192:195], v[122:125]
	v_mfma_f32_16x16x32_bf16 v[114:117], v[146:149], v[196:199], v[114:117]
	v_mfma_f32_16x16x32_bf16 v[114:117], v[150:153], v[200:203], v[114:117]
	v_mfma_f32_16x16x32_bf16 v[106:109], v[146:149], v[232:235], v[106:109]
	v_mfma_f32_16x16x32_bf16 v[106:109], v[150:153], v[236:239], v[106:109]
	v_mfma_f32_16x16x32_bf16 v[98:101], v[146:149], v[240:243], v[98:101]
	v_mfma_f32_16x16x32_bf16 v[98:101], v[150:153], v[244:247], v[98:101]
	v_mfma_f32_16x16x32_bf16 v[42:45], v[154:157], v[240:243], v[42:45]
	v_mfma_f32_16x16x32_bf16 v[42:45], v[184:187], v[244:247], v[42:45]
	v_mfma_f32_16x16x32_bf16 v[70:73], v[154:157], v[232:235], v[70:73]
	v_mfma_f32_16x16x32_bf16 v[70:73], v[184:187], v[236:239], v[70:73]
	v_mfma_f32_16x16x32_bf16 v[90:93], v[154:157], v[196:199], v[90:93]
	v_mfma_f32_16x16x32_bf16 v[90:93], v[184:187], v[200:203], v[90:93]
	v_mfma_f32_16x16x32_bf16 v[82:85], v[154:157], v[188:191], v[82:85]
	v_mfma_f32_16x16x32_bf16 v[82:85], v[184:187], v[192:195], v[82:85]
	s_setprio 0
	s_barrier
	s_add_i32 s12, s67, s33
	v_lshl_add_u64 v[162:163], s[20:21], 0, v[0:1]
	s_mov_b32 m0, s12
	ds_read_b128 v[188:191], v230 offset:16384
	ds_read_b128 v[192:195], v230 offset:17408
	ds_read_b128 v[196:199], v230 offset:18432
	ds_read_b128 v[200:203], v230 offset:19456
	ds_read_b128 v[232:235], v230 offset:20480
	ds_read_b128 v[236:239], v230 offset:21504
	ds_read_b128 v[240:243], v230 offset:22528
	ds_read_b128 v[244:247], v230 offset:23552
	global_load_lds_dwordx4 v[162:163], off
	s_add_i32 m0, s12, 0x2000
	s_add_u32 s12, s20, 0x160000
	v_lshl_add_u64 v[164:165], s[20:21], 0, v[158:159]
	s_addc_u32 s13, s21, 0
	s_add_i32 s67, s68, s33
	global_load_lds_dwordx4 v[164:165], off
	s_mov_b32 m0, s67
	v_lshl_add_u64 v[168:169], s[22:23], 0, v[160:161]
	global_load_lds_dwordx4 v0, s[12:13]
	s_add_i32 m0, s67, 0x2000
	s_nop 0
	global_load_lds_dwordx4 v158, s[12:13]
	v_lshl_add_u64 v[166:167], s[22:23], 0, v[174:175]
	s_mov_b32 m0, s28
	s_nop 0
	global_load_lds_dwordx4 v[166:167], off
	s_mov_b32 m0, s29
	s_nop 0
	global_load_lds_dwordx4 v[168:169], off
	s_waitcnt vmcnt(8)
	s_waitcnt lgkmcnt(0)
	s_barrier
	s_setprio 1
	s_waitcnt lgkmcnt(0)
	v_mfma_f32_16x16x32_bf16 v[94:97], v[130:133], v[188:191], v[94:97]
	v_mfma_f32_16x16x32_bf16 v[94:97], v[134:137], v[192:195], v[94:97]
	v_mfma_f32_16x16x32_bf16 v[62:65], v[130:133], v[196:199], v[62:65]
	v_mfma_f32_16x16x32_bf16 v[62:65], v[134:137], v[200:203], v[62:65]
	v_mfma_f32_16x16x32_bf16 v[46:49], v[130:133], v[232:235], v[46:49]
	v_mfma_f32_16x16x32_bf16 v[46:49], v[134:137], v[236:239], v[46:49]
	v_mfma_f32_16x16x32_bf16 v[22:25], v[130:133], v[240:243], v[22:25]
	v_mfma_f32_16x16x32_bf16 v[22:25], v[134:137], v[244:247], v[22:25]
	v_mfma_f32_16x16x32_bf16 v[2:5], v[138:141], v[240:243], v[2:5]
	v_mfma_f32_16x16x32_bf16 v[2:5], v[142:145], v[244:247], v[2:5]
	v_mfma_f32_16x16x32_bf16 v[10:13], v[138:141], v[232:235], v[10:13]
	v_mfma_f32_16x16x32_bf16 v[10:13], v[142:145], v[236:239], v[10:13]
	v_mfma_f32_16x16x32_bf16 v[30:33], v[138:141], v[196:199], v[30:33]
	v_mfma_f32_16x16x32_bf16 v[30:33], v[142:145], v[200:203], v[30:33]
	v_mfma_f32_16x16x32_bf16 v[50:53], v[138:141], v[188:191], v[50:53]
	v_mfma_f32_16x16x32_bf16 v[50:53], v[142:145], v[192:195], v[50:53]
	v_mfma_f32_16x16x32_bf16 v[78:81], v[146:149], v[188:191], v[78:81]
	v_mfma_f32_16x16x32_bf16 v[78:81], v[150:153], v[192:195], v[78:81]
	v_mfma_f32_16x16x32_bf16 v[54:57], v[146:149], v[196:199], v[54:57]
	v_mfma_f32_16x16x32_bf16 v[54:57], v[150:153], v[200:203], v[54:57]
	v_mfma_f32_16x16x32_bf16 v[26:29], v[146:149], v[232:235], v[26:29]
	v_mfma_f32_16x16x32_bf16 v[26:29], v[150:153], v[236:239], v[26:29]
	v_mfma_f32_16x16x32_bf16 v[18:21], v[146:149], v[240:243], v[18:21]
	v_mfma_f32_16x16x32_bf16 v[18:21], v[150:153], v[244:247], v[18:21]
	v_mfma_f32_16x16x32_bf16 v[6:9], v[154:157], v[240:243], v[6:9]
	v_mfma_f32_16x16x32_bf16 v[6:9], v[184:187], v[244:247], v[6:9]
	v_mfma_f32_16x16x32_bf16 v[14:17], v[154:157], v[232:235], v[14:17]
	v_mfma_f32_16x16x32_bf16 v[14:17], v[184:187], v[236:239], v[14:17]
	v_mfma_f32_16x16x32_bf16 v[34:37], v[154:157], v[196:199], v[34:37]
	v_mfma_f32_16x16x32_bf16 v[34:37], v[184:187], v[200:203], v[34:37]
	v_mfma_f32_16x16x32_bf16 v[58:61], v[154:157], v[188:191], v[58:61]
	v_mfma_f32_16x16x32_bf16 v[58:61], v[184:187], v[192:195], v[58:61]
	s_setprio 0
	s_barrier
	s_add_i32 s67, 0, 0x18000
	s_add_i32 s68, 0, 0x1c000
	v_add_u32_e32 v142, s67, v205
	v_add_u32_e32 v170, s68, v205
	ds_read_b128 v[130:133], v142
	ds_read_b128 v[134:137], v142 offset:1024
	ds_read_b128 v[138:141], v142 offset:2048
	ds_read_b128 v[142:145], v142 offset:3072
	ds_read_b128 v[146:149], v170
	ds_read_b128 v[150:153], v170 offset:1024
	ds_read_b128 v[154:157], v170 offset:2048
	ds_read_b128 v[184:187], v170 offset:3072
	s_add_u32 s12, s22, 0x160000
	s_addc_u32 s13, s23, 0
	s_mov_b32 m0, s34
	ds_read_b128 v[188:191], v230 offset:32768
	ds_read_b128 v[192:195], v230 offset:33792
	ds_read_b128 v[196:199], v230 offset:34816
	ds_read_b128 v[200:203], v230 offset:35840
	ds_read_b128 v[232:235], v230 offset:36864
	ds_read_b128 v[236:239], v230 offset:37888
	ds_read_b128 v[240:243], v230 offset:38912
	ds_read_b128 v[244:247], v230 offset:39936
	global_load_lds_dwordx4 v174, s[12:13]
	s_mov_b32 m0, s35
	s_nop 0
	global_load_lds_dwordx4 v160, s[12:13]
	s_waitcnt vmcnt(8)
	s_waitcnt lgkmcnt(0)
	s_barrier
	s_setprio 1
	s_waitcnt lgkmcnt(0)
	v_mfma_f32_16x16x32_bf16 v[126:129], v[130:133], v[188:191], v[126:129]
	v_mfma_f32_16x16x32_bf16 v[126:129], v[134:137], v[192:195], v[126:129]
	v_mfma_f32_16x16x32_bf16 v[118:121], v[130:133], v[196:199], v[118:121]
	v_mfma_f32_16x16x32_bf16 v[118:121], v[134:137], v[200:203], v[118:121]
	v_mfma_f32_16x16x32_bf16 v[110:113], v[130:133], v[232:235], v[110:113]
	v_mfma_f32_16x16x32_bf16 v[110:113], v[134:137], v[236:239], v[110:113]
	v_mfma_f32_16x16x32_bf16 v[102:105], v[130:133], v[240:243], v[102:105]
	v_mfma_f32_16x16x32_bf16 v[102:105], v[134:137], v[244:247], v[102:105]
	v_mfma_f32_16x16x32_bf16 v[38:41], v[138:141], v[240:243], v[38:41]
	v_mfma_f32_16x16x32_bf16 v[38:41], v[142:145], v[244:247], v[38:41]
	v_mfma_f32_16x16x32_bf16 v[66:69], v[138:141], v[232:235], v[66:69]
	v_mfma_f32_16x16x32_bf16 v[66:69], v[142:145], v[236:239], v[66:69]
	v_mfma_f32_16x16x32_bf16 v[86:89], v[138:141], v[196:199], v[86:89]
	v_mfma_f32_16x16x32_bf16 v[86:89], v[142:145], v[200:203], v[86:89]
	v_mfma_f32_16x16x32_bf16 v[74:77], v[138:141], v[188:191], v[74:77]
	v_mfma_f32_16x16x32_bf16 v[74:77], v[142:145], v[192:195], v[74:77]
	v_mfma_f32_16x16x32_bf16 v[122:125], v[146:149], v[188:191], v[122:125]
	v_mfma_f32_16x16x32_bf16 v[122:125], v[150:153], v[192:195], v[122:125]
	v_mfma_f32_16x16x32_bf16 v[114:117], v[146:149], v[196:199], v[114:117]
	v_mfma_f32_16x16x32_bf16 v[114:117], v[150:153], v[200:203], v[114:117]
	v_mfma_f32_16x16x32_bf16 v[106:109], v[146:149], v[232:235], v[106:109]
	v_mfma_f32_16x16x32_bf16 v[106:109], v[150:153], v[236:239], v[106:109]
	v_mfma_f32_16x16x32_bf16 v[98:101], v[146:149], v[240:243], v[98:101]
	v_mfma_f32_16x16x32_bf16 v[98:101], v[150:153], v[244:247], v[98:101]
	v_mfma_f32_16x16x32_bf16 v[42:45], v[154:157], v[240:243], v[42:45]
	v_mfma_f32_16x16x32_bf16 v[42:45], v[184:187], v[244:247], v[42:45]
	v_mfma_f32_16x16x32_bf16 v[70:73], v[154:157], v[232:235], v[70:73]
	v_mfma_f32_16x16x32_bf16 v[70:73], v[184:187], v[236:239], v[70:73]
	v_mfma_f32_16x16x32_bf16 v[90:93], v[154:157], v[196:199], v[90:93]
	v_mfma_f32_16x16x32_bf16 v[90:93], v[184:187], v[200:203], v[90:93]
	v_mfma_f32_16x16x32_bf16 v[82:85], v[154:157], v[188:191], v[82:85]
	v_mfma_f32_16x16x32_bf16 v[82:85], v[184:187], v[192:195], v[82:85]
	s_setprio 0
	s_barrier
	s_add_i32 s12, s67, s33
	v_lshl_add_u64 v[162:163], v[162:163], 0, s[30:31]
	s_mov_b32 m0, s12
	ds_read_b128 v[188:191], v230 offset:49152
	ds_read_b128 v[192:195], v230 offset:50176
	ds_read_b128 v[196:199], v230 offset:51200
	ds_read_b128 v[200:203], v230 offset:52224
	ds_read_b128 v[232:235], v230 offset:53248
	ds_read_b128 v[236:239], v230 offset:54272
	ds_read_b128 v[240:243], v230 offset:55296
	ds_read_b128 v[244:247], v230 offset:56320
	global_load_lds_dwordx4 v[162:163], off
	s_add_i32 m0, s12, 0x2000
	s_add_u32 s12, s20, 0x160080
	v_lshl_add_u64 v[162:163], v[164:165], 0, s[30:31]
	s_addc_u32 s13, s21, 0
	s_add_i32 s20, s68, s33
	global_load_lds_dwordx4 v[162:163], off
	s_mov_b32 m0, s20
	s_nop 0
	global_load_lds_dwordx4 v0, s[12:13]
	s_add_i32 m0, s20, 0x2000
	s_nop 0
	global_load_lds_dwordx4 v158, s[12:13]
	v_lshl_add_u64 v[162:163], v[166:167], 0, s[30:31]
	s_mov_b32 m0, s55
	s_nop 0
	global_load_lds_dwordx4 v[162:163], off
	v_lshl_add_u64 v[162:163], v[168:169], 0, s[30:31]
	s_mov_b32 m0, s56
	s_nop 0
	global_load_lds_dwordx4 v[162:163], off
	s_waitcnt vmcnt(8)
	s_waitcnt lgkmcnt(0)
	s_barrier
	s_setprio 1
	s_waitcnt lgkmcnt(0)
	v_mfma_f32_16x16x32_bf16 v[94:97], v[130:133], v[188:191], v[94:97]
	v_mfma_f32_16x16x32_bf16 v[94:97], v[134:137], v[192:195], v[94:97]
	v_mfma_f32_16x16x32_bf16 v[62:65], v[130:133], v[196:199], v[62:65]
	v_mfma_f32_16x16x32_bf16 v[62:65], v[134:137], v[200:203], v[62:65]
	v_mfma_f32_16x16x32_bf16 v[46:49], v[130:133], v[232:235], v[46:49]
	v_mfma_f32_16x16x32_bf16 v[46:49], v[134:137], v[236:239], v[46:49]
	v_mfma_f32_16x16x32_bf16 v[22:25], v[130:133], v[240:243], v[22:25]
	v_mfma_f32_16x16x32_bf16 v[22:25], v[134:137], v[244:247], v[22:25]
	v_mfma_f32_16x16x32_bf16 v[2:5], v[138:141], v[240:243], v[2:5]
	v_mfma_f32_16x16x32_bf16 v[2:5], v[142:145], v[244:247], v[2:5]
	v_mfma_f32_16x16x32_bf16 v[10:13], v[138:141], v[232:235], v[10:13]
	v_mfma_f32_16x16x32_bf16 v[10:13], v[142:145], v[236:239], v[10:13]
	v_mfma_f32_16x16x32_bf16 v[30:33], v[138:141], v[196:199], v[30:33]
	v_mfma_f32_16x16x32_bf16 v[30:33], v[142:145], v[200:203], v[30:33]
	v_mfma_f32_16x16x32_bf16 v[50:53], v[138:141], v[188:191], v[50:53]
	v_mfma_f32_16x16x32_bf16 v[50:53], v[142:145], v[192:195], v[50:53]
	v_mfma_f32_16x16x32_bf16 v[78:81], v[146:149], v[188:191], v[78:81]
	v_mfma_f32_16x16x32_bf16 v[78:81], v[150:153], v[192:195], v[78:81]
	v_mfma_f32_16x16x32_bf16 v[54:57], v[146:149], v[196:199], v[54:57]
	v_mfma_f32_16x16x32_bf16 v[54:57], v[150:153], v[200:203], v[54:57]
	v_mfma_f32_16x16x32_bf16 v[26:29], v[146:149], v[232:235], v[26:29]
	v_mfma_f32_16x16x32_bf16 v[26:29], v[150:153], v[236:239], v[26:29]
	v_mfma_f32_16x16x32_bf16 v[18:21], v[146:149], v[240:243], v[18:21]
	v_mfma_f32_16x16x32_bf16 v[18:21], v[150:153], v[244:247], v[18:21]
	v_mfma_f32_16x16x32_bf16 v[6:9], v[154:157], v[240:243], v[6:9]
	v_mfma_f32_16x16x32_bf16 v[6:9], v[184:187], v[244:247], v[6:9]
	v_mfma_f32_16x16x32_bf16 v[14:17], v[154:157], v[232:235], v[14:17]
	v_mfma_f32_16x16x32_bf16 v[14:17], v[184:187], v[236:239], v[14:17]
	v_mfma_f32_16x16x32_bf16 v[34:37], v[154:157], v[196:199], v[34:37]
	v_mfma_f32_16x16x32_bf16 v[34:37], v[184:187], v[200:203], v[34:37]
	v_mfma_f32_16x16x32_bf16 v[58:61], v[154:157], v[188:191], v[58:61]
	v_mfma_f32_16x16x32_bf16 v[58:61], v[184:187], v[192:195], v[58:61]
	s_setprio 0
	s_barrier
	s_add_i32 s19, s19, 2
	s_add_u32 s15, s15, 0x100
	s_addc_u32 s18, s18, 0
	s_cmpk_gt_u32 s19, 0x55
	s_mov_b64 s[12:13], s[16:17]
	s_cbranch_scc0 .LBB0_493
	v_readlane_b32 s12, v253, 2
	v_readlane_b32 s13, v253, 3
	s_and_b64 vcc, exec, s[12:13]
	s_cbranch_vccz .LBB0_496
	s_barrier

.LBB0_641:
	s_add_u32 s28, s26, 0xfffc0080
	s_addc_u32 s29, s27, -1
	s_add_i32 s57, 0, 0x10000
	s_cmp_eq_u32 s56, 12
	s_cselect_b32 s43, s15, s29
	s_cselect_b32 s42, s19, s28
	s_cselect_b32 s29, s11, s55
	s_cselect_b32 s28, s53, s54
	s_add_i32 s60, 0, 0x14000
	v_add_u32_e32 v152, s57, v159
	v_add_u32_e32 v156, s60, v159
	ds_read_b128 v[140:143], v152
	ds_read_b128 v[144:147], v152 offset:1024
	ds_read_b128 v[148:151], v152 offset:2048
	ds_read_b128 v[152:155], v152 offset:3072
	ds_read_b128 v[176:179], v156
	ds_read_b128 v[180:183], v156 offset:1024
	ds_read_b128 v[184:187], v156 offset:2048
	ds_read_b128 v[188:191], v156 offset:3072
	s_add_i32 m0, s44, 0xc000
	ds_read_b128 v[192:195], v174
	ds_read_b128 v[196:199], v174 offset:1024
	ds_read_b128 v[200:203], v174 offset:2048
	ds_read_b128 v[204:207], v174 offset:3072
	ds_read_b128 v[208:211], v174 offset:4096
	ds_read_b128 v[224:227], v174 offset:5120
	ds_read_b128 v[228:231], v174 offset:6144
	ds_read_b128 v[232:235], v174 offset:7168
	global_load_lds_dwordx4 v136, s[26:27]
	s_add_i32 m0, s44, 0xe000
	s_nop 0
	global_load_lds_dwordx4 v138, s[26:27]
	s_waitcnt vmcnt(8)
	s_waitcnt lgkmcnt(0)
	s_barrier
	s_setprio 1
	s_waitcnt lgkmcnt(0)
	v_mfma_i32_16x16x64_i8 v[126:129], v[140:143], v[192:195], v[126:129]
	v_mfma_i32_16x16x64_i8 v[126:129], v[144:147], v[196:199], v[126:129]
	v_mfma_i32_16x16x64_i8 v[110:113], v[140:143], v[200:203], v[110:113]
	v_mfma_i32_16x16x64_i8 v[110:113], v[144:147], v[204:207], v[110:113]
	v_mfma_i32_16x16x64_i8 v[94:97], v[140:143], v[208:211], v[94:97]
	v_mfma_i32_16x16x64_i8 v[94:97], v[144:147], v[224:227], v[94:97]
	v_mfma_i32_16x16x64_i8 v[78:81], v[140:143], v[228:231], v[78:81]
	v_mfma_i32_16x16x64_i8 v[78:81], v[144:147], v[232:235], v[78:81]
	v_mfma_i32_16x16x64_i8 v[74:77], v[148:151], v[228:231], v[74:77]
	v_mfma_i32_16x16x64_i8 v[74:77], v[152:155], v[232:235], v[74:77]
	v_mfma_i32_16x16x64_i8 v[90:93], v[148:151], v[208:211], v[90:93]
	v_mfma_i32_16x16x64_i8 v[90:93], v[152:155], v[224:227], v[90:93]
	v_mfma_i32_16x16x64_i8 v[106:109], v[148:151], v[200:203], v[106:109]
	v_mfma_i32_16x16x64_i8 v[106:109], v[152:155], v[204:207], v[106:109]
	v_mfma_i32_16x16x64_i8 v[122:125], v[148:151], v[192:195], v[122:125]
	v_mfma_i32_16x16x64_i8 v[122:125], v[152:155], v[196:199], v[122:125]
	v_mfma_i32_16x16x64_i8 v[118:121], v[176:179], v[192:195], v[118:121]
	v_mfma_i32_16x16x64_i8 v[118:121], v[180:183], v[196:199], v[118:121]
	v_mfma_i32_16x16x64_i8 v[102:105], v[176:179], v[200:203], v[102:105]
	v_mfma_i32_16x16x64_i8 v[102:105], v[180:183], v[204:207], v[102:105]
	v_mfma_i32_16x16x64_i8 v[86:89], v[176:179], v[208:211], v[86:89]
	v_mfma_i32_16x16x64_i8 v[86:89], v[180:183], v[224:227], v[86:89]
	v_mfma_i32_16x16x64_i8 v[70:73], v[176:179], v[228:231], v[70:73]
	v_mfma_i32_16x16x64_i8 v[70:73], v[180:183], v[232:235], v[70:73]
	v_mfma_i32_16x16x64_i8 v[66:69], v[184:187], v[228:231], v[66:69]
	v_mfma_i32_16x16x64_i8 v[66:69], v[188:191], v[232:235], v[66:69]
	v_mfma_i32_16x16x64_i8 v[82:85], v[184:187], v[208:211], v[82:85]
	v_mfma_i32_16x16x64_i8 v[82:85], v[188:191], v[224:227], v[82:85]
	v_mfma_i32_16x16x64_i8 v[98:101], v[184:187], v[200:203], v[98:101]
	v_mfma_i32_16x16x64_i8 v[98:101], v[188:191], v[204:207], v[98:101]
	v_mfma_i32_16x16x64_i8 v[114:117], v[184:187], v[192:195], v[114:117]
	v_mfma_i32_16x16x64_i8 v[114:117], v[188:191], v[196:199], v[114:117]
	s_setprio 0
	s_barrier
	s_add_i32 s57, s57, s33
	v_lshl_add_u64 v[156:157], s[28:29], 0, v[0:1]
	s_mov_b32 m0, s57
	ds_read_b128 v[192:195], v174 offset:16384
	ds_read_b128 v[196:199], v174 offset:17408
	ds_read_b128 v[200:203], v174 offset:18432
	ds_read_b128 v[204:207], v174 offset:19456
	ds_read_b128 v[208:211], v174 offset:20480
	ds_read_b128 v[224:227], v174 offset:21504
	ds_read_b128 v[228:231], v174 offset:22528
	ds_read_b128 v[232:235], v174 offset:23552
	global_load_lds_dwordx4 v[156:157], off
	s_add_i32 m0, s57, 0x2000
	s_add_u32 s58, s28, 0x40000
	v_lshl_add_u64 v[162:163], s[28:29], 0, v[130:131]
	s_addc_u32 s59, s29, 0
	s_add_i32 s57, s60, s33
	global_load_lds_dwordx4 v[162:163], off
	s_mov_b32 m0, s57
	v_lshl_add_u64 v[166:167], s[42:43], 0, v[132:133]
	global_load_lds_dwordx4 v0, s[58:59]
	s_add_i32 m0, s57, 0x2000
	s_nop 0
	global_load_lds_dwordx4 v130, s[58:59]
	v_lshl_add_u64 v[164:165], s[42:43], 0, v[134:135]
	s_mov_b32 m0, s44
	s_nop 0
	global_load_lds_dwordx4 v[164:165], off
	s_mov_b32 m0, s45
	s_nop 0
	global_load_lds_dwordx4 v[166:167], off
	s_waitcnt vmcnt(8)
	s_waitcnt lgkmcnt(0)
	s_barrier
	s_setprio 1
	s_waitcnt lgkmcnt(0)
	v_mfma_i32_16x16x64_i8 v[62:65], v[140:143], v[192:195], v[62:65]
	v_mfma_i32_16x16x64_i8 v[62:65], v[144:147], v[196:199], v[62:65]
	v_mfma_i32_16x16x64_i8 v[46:49], v[140:143], v[200:203], v[46:49]
	v_mfma_i32_16x16x64_i8 v[46:49], v[144:147], v[204:207], v[46:49]
	v_mfma_i32_16x16x64_i8 v[30:33], v[140:143], v[208:211], v[30:33]
	v_mfma_i32_16x16x64_i8 v[30:33], v[144:147], v[224:227], v[30:33]
	v_mfma_i32_16x16x64_i8 v[14:17], v[140:143], v[228:231], v[14:17]
	v_mfma_i32_16x16x64_i8 v[14:17], v[144:147], v[232:235], v[14:17]
	v_mfma_i32_16x16x64_i8 v[10:13], v[148:151], v[228:231], v[10:13]
	v_mfma_i32_16x16x64_i8 v[10:13], v[152:155], v[232:235], v[10:13]
	v_mfma_i32_16x16x64_i8 v[26:29], v[148:151], v[208:211], v[26:29]
	v_mfma_i32_16x16x64_i8 v[26:29], v[152:155], v[224:227], v[26:29]
	v_mfma_i32_16x16x64_i8 v[42:45], v[148:151], v[200:203], v[42:45]
	v_mfma_i32_16x16x64_i8 v[42:45], v[152:155], v[204:207], v[42:45]
	v_mfma_i32_16x16x64_i8 v[58:61], v[148:151], v[192:195], v[58:61]
	v_mfma_i32_16x16x64_i8 v[58:61], v[152:155], v[196:199], v[58:61]
	v_mfma_i32_16x16x64_i8 v[54:57], v[176:179], v[192:195], v[54:57]
	v_mfma_i32_16x16x64_i8 v[54:57], v[180:183], v[196:199], v[54:57]
	v_mfma_i32_16x16x64_i8 v[38:41], v[176:179], v[200:203], v[38:41]
	v_mfma_i32_16x16x64_i8 v[38:41], v[180:183], v[204:207], v[38:41]
	v_mfma_i32_16x16x64_i8 v[22:25], v[176:179], v[208:211], v[22:25]
	v_mfma_i32_16x16x64_i8 v[22:25], v[180:183], v[224:227], v[22:25]
	v_mfma_i32_16x16x64_i8 v[6:9], v[176:179], v[228:231], v[6:9]
	v_mfma_i32_16x16x64_i8 v[6:9], v[180:183], v[232:235], v[6:9]
	v_mfma_i32_16x16x64_i8 v[2:5], v[184:187], v[228:231], v[2:5]
	v_mfma_i32_16x16x64_i8 v[2:5], v[188:191], v[232:235], v[2:5]
	v_mfma_i32_16x16x64_i8 v[18:21], v[184:187], v[208:211], v[18:21]
	v_mfma_i32_16x16x64_i8 v[18:21], v[188:191], v[224:227], v[18:21]
	v_mfma_i32_16x16x64_i8 v[34:37], v[184:187], v[200:203], v[34:37]
	v_mfma_i32_16x16x64_i8 v[34:37], v[188:191], v[204:207], v[34:37]
	v_mfma_i32_16x16x64_i8 v[50:53], v[184:187], v[192:195], v[50:53]
	v_mfma_i32_16x16x64_i8 v[50:53], v[188:191], v[196:199], v[50:53]
	s_setprio 0
	s_barrier
	s_add_i32 s57, 0, 0x18000
	s_add_i32 s58, 0, 0x1c000
	v_add_u32_e32 v152, s57, v159
	v_add_u32_e32 v168, s58, v159
	ds_read_b128 v[140:143], v152
	ds_read_b128 v[144:147], v152 offset:1024
	ds_read_b128 v[148:151], v152 offset:2048
	ds_read_b128 v[152:155], v152 offset:3072
	ds_read_b128 v[176:179], v168
	ds_read_b128 v[180:183], v168 offset:1024
	ds_read_b128 v[184:187], v168 offset:2048
	ds_read_b128 v[188:191], v168 offset:3072
	s_add_u32 s42, s42, 0x40000
	s_addc_u32 s43, s43, 0
	s_mov_b32 m0, s46
	ds_read_b128 v[192:195], v174 offset:32768
	ds_read_b128 v[196:199], v174 offset:33792
	ds_read_b128 v[200:203], v174 offset:34816
	ds_read_b128 v[204:207], v174 offset:35840
	ds_read_b128 v[208:211], v174 offset:36864
	ds_read_b128 v[224:227], v174 offset:37888
	ds_read_b128 v[228:231], v174 offset:38912
	ds_read_b128 v[232:235], v174 offset:39936
	global_load_lds_dwordx4 v134, s[42:43]
	s_mov_b32 m0, s47
	s_nop 0
	global_load_lds_dwordx4 v132, s[42:43]
	s_waitcnt vmcnt(8)
	s_waitcnt lgkmcnt(0)
	s_barrier
	s_setprio 1
	s_waitcnt lgkmcnt(0)
	v_mfma_i32_16x16x64_i8 v[126:129], v[140:143], v[192:195], v[126:129]
	v_mfma_i32_16x16x64_i8 v[126:129], v[144:147], v[196:199], v[126:129]
	v_mfma_i32_16x16x64_i8 v[110:113], v[140:143], v[200:203], v[110:113]
	v_mfma_i32_16x16x64_i8 v[110:113], v[144:147], v[204:207], v[110:113]
	v_mfma_i32_16x16x64_i8 v[94:97], v[140:143], v[208:211], v[94:97]
	v_mfma_i32_16x16x64_i8 v[94:97], v[144:147], v[224:227], v[94:97]
	v_mfma_i32_16x16x64_i8 v[78:81], v[140:143], v[228:231], v[78:81]
	v_mfma_i32_16x16x64_i8 v[78:81], v[144:147], v[232:235], v[78:81]
	v_mfma_i32_16x16x64_i8 v[74:77], v[148:151], v[228:231], v[74:77]
	v_mfma_i32_16x16x64_i8 v[74:77], v[152:155], v[232:235], v[74:77]
	v_mfma_i32_16x16x64_i8 v[90:93], v[148:151], v[208:211], v[90:93]
	v_mfma_i32_16x16x64_i8 v[90:93], v[152:155], v[224:227], v[90:93]
	v_mfma_i32_16x16x64_i8 v[106:109], v[148:151], v[200:203], v[106:109]
	v_mfma_i32_16x16x64_i8 v[106:109], v[152:155], v[204:207], v[106:109]
	v_mfma_i32_16x16x64_i8 v[122:125], v[148:151], v[192:195], v[122:125]
	v_mfma_i32_16x16x64_i8 v[122:125], v[152:155], v[196:199], v[122:125]
	v_mfma_i32_16x16x64_i8 v[118:121], v[176:179], v[192:195], v[118:121]
	v_mfma_i32_16x16x64_i8 v[118:121], v[180:183], v[196:199], v[118:121]
	v_mfma_i32_16x16x64_i8 v[102:105], v[176:179], v[200:203], v[102:105]
	v_mfma_i32_16x16x64_i8 v[102:105], v[180:183], v[204:207], v[102:105]
	v_mfma_i32_16x16x64_i8 v[86:89], v[176:179], v[208:211], v[86:89]
	v_mfma_i32_16x16x64_i8 v[86:89], v[180:183], v[224:227], v[86:89]
	v_mfma_i32_16x16x64_i8 v[70:73], v[176:179], v[228:231], v[70:73]
	v_mfma_i32_16x16x64_i8 v[70:73], v[180:183], v[232:235], v[70:73]
	v_mfma_i32_16x16x64_i8 v[66:69], v[184:187], v[228:231], v[66:69]
	v_mfma_i32_16x16x64_i8 v[66:69], v[188:191], v[232:235], v[66:69]
	v_mfma_i32_16x16x64_i8 v[82:85], v[184:187], v[208:211], v[82:85]
	v_mfma_i32_16x16x64_i8 v[82:85], v[188:191], v[224:227], v[82:85]
	v_mfma_i32_16x16x64_i8 v[98:101], v[184:187], v[200:203], v[98:101]
	v_mfma_i32_16x16x64_i8 v[98:101], v[188:191], v[204:207], v[98:101]
	v_mfma_i32_16x16x64_i8 v[114:117], v[184:187], v[192:195], v[114:117]
	v_mfma_i32_16x16x64_i8 v[114:117], v[188:191], v[196:199], v[114:117]
	s_setprio 0
	s_barrier
	s_add_i32 s42, s57, s33
	v_lshl_add_u64 v[156:157], v[156:157], 0, s[30:31]
	s_mov_b32 m0, s42
	ds_read_b128 v[192:195], v174 offset:49152
	ds_read_b128 v[196:199], v174 offset:50176
	ds_read_b128 v[200:203], v174 offset:51200
	ds_read_b128 v[204:207], v174 offset:52224
	ds_read_b128 v[208:211], v174 offset:53248
	ds_read_b128 v[224:227], v174 offset:54272
	ds_read_b128 v[228:231], v174 offset:55296
	ds_read_b128 v[232:235], v174 offset:56320
	global_load_lds_dwordx4 v[156:157], off
	s_add_i32 m0, s42, 0x2000
	s_add_u32 s28, s28, 0x40080
	v_lshl_add_u64 v[156:157], v[162:163], 0, s[30:31]
	s_addc_u32 s29, s29, 0
	s_add_i32 s42, s58, s33
	global_load_lds_dwordx4 v[156:157], off
	s_mov_b32 m0, s42
	s_nop 0
	global_load_lds_dwordx4 v0, s[28:29]
	s_add_i32 m0, s42, 0x2000
	s_nop 0
	global_load_lds_dwordx4 v130, s[28:29]
	v_lshl_add_u64 v[156:157], v[164:165], 0, s[30:31]
	s_mov_b32 m0, s48
	s_nop 0
	global_load_lds_dwordx4 v[156:157], off
	v_lshl_add_u64 v[156:157], v[166:167], 0, s[30:31]
	s_mov_b32 m0, s49
	s_nop 0
	global_load_lds_dwordx4 v[156:157], off
	s_waitcnt vmcnt(8)
	s_waitcnt lgkmcnt(0)
	s_barrier
	s_setprio 1
	s_waitcnt lgkmcnt(0)
	v_mfma_i32_16x16x64_i8 v[62:65], v[140:143], v[192:195], v[62:65]
	v_mfma_i32_16x16x64_i8 v[62:65], v[144:147], v[196:199], v[62:65]
	v_mfma_i32_16x16x64_i8 v[46:49], v[140:143], v[200:203], v[46:49]
	v_mfma_i32_16x16x64_i8 v[46:49], v[144:147], v[204:207], v[46:49]
	v_mfma_i32_16x16x64_i8 v[30:33], v[140:143], v[208:211], v[30:33]
	v_mfma_i32_16x16x64_i8 v[30:33], v[144:147], v[224:227], v[30:33]
	v_mfma_i32_16x16x64_i8 v[14:17], v[140:143], v[228:231], v[14:17]
	v_mfma_i32_16x16x64_i8 v[14:17], v[144:147], v[232:235], v[14:17]
	v_mfma_i32_16x16x64_i8 v[10:13], v[148:151], v[228:231], v[10:13]
	v_mfma_i32_16x16x64_i8 v[10:13], v[152:155], v[232:235], v[10:13]
	v_mfma_i32_16x16x64_i8 v[26:29], v[148:151], v[208:211], v[26:29]
	v_mfma_i32_16x16x64_i8 v[26:29], v[152:155], v[224:227], v[26:29]
	v_mfma_i32_16x16x64_i8 v[42:45], v[148:151], v[200:203], v[42:45]
	v_mfma_i32_16x16x64_i8 v[42:45], v[152:155], v[204:207], v[42:45]
	v_mfma_i32_16x16x64_i8 v[58:61], v[148:151], v[192:195], v[58:61]
	v_mfma_i32_16x16x64_i8 v[58:61], v[152:155], v[196:199], v[58:61]
	v_mfma_i32_16x16x64_i8 v[54:57], v[176:179], v[192:195], v[54:57]
	v_mfma_i32_16x16x64_i8 v[54:57], v[180:183], v[196:199], v[54:57]
	v_mfma_i32_16x16x64_i8 v[38:41], v[176:179], v[200:203], v[38:41]
	v_mfma_i32_16x16x64_i8 v[38:41], v[180:183], v[204:207], v[38:41]
	v_mfma_i32_16x16x64_i8 v[22:25], v[176:179], v[208:211], v[22:25]
	v_mfma_i32_16x16x64_i8 v[22:25], v[180:183], v[224:227], v[22:25]
	v_mfma_i32_16x16x64_i8 v[6:9], v[176:179], v[228:231], v[6:9]
	v_mfma_i32_16x16x64_i8 v[6:9], v[180:183], v[232:235], v[6:9]
	v_mfma_i32_16x16x64_i8 v[2:5], v[184:187], v[228:231], v[2:5]
	v_mfma_i32_16x16x64_i8 v[2:5], v[188:191], v[232:235], v[2:5]
	v_mfma_i32_16x16x64_i8 v[18:21], v[184:187], v[208:211], v[18:21]
	v_mfma_i32_16x16x64_i8 v[18:21], v[188:191], v[224:227], v[18:21]
	v_mfma_i32_16x16x64_i8 v[34:37], v[184:187], v[200:203], v[34:37]
	v_mfma_i32_16x16x64_i8 v[34:37], v[188:191], v[204:207], v[34:37]
	v_mfma_i32_16x16x64_i8 v[50:53], v[184:187], v[192:195], v[50:53]
	v_mfma_i32_16x16x64_i8 v[50:53], v[188:191], v[196:199], v[50:53]
	s_setprio 0
	s_barrier
	s_add_i32 s56, s56, 2
	s_add_u32 s26, s26, 0x100
	s_addc_u32 s27, s27, 0
	s_add_u32 s54, s54, 0x100
	s_addc_u32 s55, s55, 0
	s_cmp_gt_u32 s56, 13
	s_cbranch_scc0 .LBB0_641
	v_readlane_b32 s26, v253, 2
	v_readlane_b32 s27, v253, 3
	s_and_b64 vcc, exec, s[26:27]
	s_cbranch_vccz .LBB0_644
	s_barrier

.LBB0_665:
	s_add_u32 s16, s6, 0xfff80080
	s_addc_u32 s17, s7, -1
	s_add_i32 s57, 0, 0x10000
	s_cmp_eq_u32 s56, 28
	s_cselect_b32 s21, s9, s17
	s_cselect_b32 s20, s18, s16
	s_cselect_b32 s17, s5, s55
	s_cselect_b32 s16, s19, s54
	s_add_i32 s60, 0, 0x14000
	v_add_u32_e32 v142, s57, v193
	v_add_u32_e32 v162, s60, v193
	ds_read_b128 v[130:133], v142
	ds_read_b128 v[134:137], v142 offset:1024
	ds_read_b128 v[138:141], v142 offset:2048
	ds_read_b128 v[142:145], v142 offset:3072
	ds_read_b128 v[158:161], v162
	ds_read_b128 v[174:177], v162 offset:1024
	ds_read_b128 v[178:181], v162 offset:2048
	ds_read_b128 v[182:185], v162 offset:3072
	s_add_i32 m0, s26, 0xc000
	ds_read_b128 v[186:189], v196
	ds_read_b128 v[198:201], v196 offset:1024
	ds_read_b128 v[202:205], v196 offset:2048
	ds_read_b128 v[206:209], v196 offset:3072
	ds_read_b128 v[224:227], v196 offset:4096
	ds_read_b128 v[228:231], v196 offset:5120
	ds_read_b128 v[232:235], v196 offset:6144
	ds_read_b128 v[236:239], v196 offset:7168
	global_load_lds_dwordx4 v154, s[6:7]
	s_add_i32 m0, s26, 0xe000
	s_nop 0
	global_load_lds_dwordx4 v156, s[6:7]
	s_waitcnt vmcnt(8)
	s_waitcnt lgkmcnt(0)
	s_barrier
	s_setprio 1
	s_waitcnt lgkmcnt(0)
	v_mfma_f32_16x16x32_bf16 v[126:129], v[130:133], v[186:189], v[126:129]
	v_mfma_f32_16x16x32_bf16 v[126:129], v[134:137], v[198:201], v[126:129]
	v_mfma_f32_16x16x32_bf16 v[110:113], v[130:133], v[202:205], v[110:113]
	v_mfma_f32_16x16x32_bf16 v[110:113], v[134:137], v[206:209], v[110:113]
	v_mfma_f32_16x16x32_bf16 v[94:97], v[130:133], v[224:227], v[94:97]
	v_mfma_f32_16x16x32_bf16 v[94:97], v[134:137], v[228:231], v[94:97]
	v_mfma_f32_16x16x32_bf16 v[78:81], v[130:133], v[232:235], v[78:81]
	v_mfma_f32_16x16x32_bf16 v[78:81], v[134:137], v[236:239], v[78:81]
	v_mfma_f32_16x16x32_bf16 v[74:77], v[138:141], v[232:235], v[74:77]
	v_mfma_f32_16x16x32_bf16 v[74:77], v[142:145], v[236:239], v[74:77]
	v_mfma_f32_16x16x32_bf16 v[90:93], v[138:141], v[224:227], v[90:93]
	v_mfma_f32_16x16x32_bf16 v[90:93], v[142:145], v[228:231], v[90:93]
	v_mfma_f32_16x16x32_bf16 v[106:109], v[138:141], v[202:205], v[106:109]
	v_mfma_f32_16x16x32_bf16 v[106:109], v[142:145], v[206:209], v[106:109]
	v_mfma_f32_16x16x32_bf16 v[122:125], v[138:141], v[186:189], v[122:125]
	v_mfma_f32_16x16x32_bf16 v[122:125], v[142:145], v[198:201], v[122:125]
	v_mfma_f32_16x16x32_bf16 v[118:121], v[158:161], v[186:189], v[118:121]
	v_mfma_f32_16x16x32_bf16 v[118:121], v[174:177], v[198:201], v[118:121]
	v_mfma_f32_16x16x32_bf16 v[102:105], v[158:161], v[202:205], v[102:105]
	v_mfma_f32_16x16x32_bf16 v[102:105], v[174:177], v[206:209], v[102:105]
	v_mfma_f32_16x16x32_bf16 v[86:89], v[158:161], v[224:227], v[86:89]
	v_mfma_f32_16x16x32_bf16 v[86:89], v[174:177], v[228:231], v[86:89]
	v_mfma_f32_16x16x32_bf16 v[70:73], v[158:161], v[232:235], v[70:73]
	v_mfma_f32_16x16x32_bf16 v[70:73], v[174:177], v[236:239], v[70:73]
	v_mfma_f32_16x16x32_bf16 v[66:69], v[178:181], v[232:235], v[66:69]
	v_mfma_f32_16x16x32_bf16 v[66:69], v[182:185], v[236:239], v[66:69]
	v_mfma_f32_16x16x32_bf16 v[82:85], v[178:181], v[224:227], v[82:85]
	v_mfma_f32_16x16x32_bf16 v[82:85], v[182:185], v[228:231], v[82:85]
	v_mfma_f32_16x16x32_bf16 v[98:101], v[178:181], v[202:205], v[98:101]
	v_mfma_f32_16x16x32_bf16 v[98:101], v[182:185], v[206:209], v[98:101]
	v_mfma_f32_16x16x32_bf16 v[114:117], v[178:181], v[186:189], v[114:117]
	v_mfma_f32_16x16x32_bf16 v[114:117], v[182:185], v[198:201], v[114:117]
	s_setprio 0
	s_barrier
	s_add_i32 s57, s57, s33
	v_lshl_add_u64 v[162:163], s[16:17], 0, v[0:1]
	s_mov_b32 m0, s57
	ds_read_b128 v[186:189], v196 offset:16384
	ds_read_b128 v[198:201], v196 offset:17408
	ds_read_b128 v[202:205], v196 offset:18432
	ds_read_b128 v[206:209], v196 offset:19456
	ds_read_b128 v[224:227], v196 offset:20480
	ds_read_b128 v[228:231], v196 offset:21504
	ds_read_b128 v[232:235], v196 offset:22528
	ds_read_b128 v[236:239], v196 offset:23552
	global_load_lds_dwordx4 v[162:163], off
	s_add_i32 m0, s57, 0x2000
	s_add_u32 s58, s16, 0x80000
	v_lshl_add_u64 v[164:165], s[16:17], 0, v[146:147]
	s_addc_u32 s59, s17, 0
	s_add_i32 s57, s60, s33
	global_load_lds_dwordx4 v[164:165], off
	s_mov_b32 m0, s57
	v_lshl_add_u64 v[168:169], s[20:21], 0, v[148:149]
	global_load_lds_dwordx4 v0, s[58:59]
	s_add_i32 m0, s57, 0x2000
	s_nop 0
	global_load_lds_dwordx4 v146, s[58:59]
	v_lshl_add_u64 v[166:167], s[20:21], 0, v[150:151]
	s_mov_b32 m0, s26
	s_nop 0
	global_load_lds_dwordx4 v[166:167], off
	s_mov_b32 m0, s27
	s_nop 0
	global_load_lds_dwordx4 v[168:169], off
	s_waitcnt vmcnt(8)
	s_waitcnt lgkmcnt(0)
	s_barrier
	s_setprio 1
	s_waitcnt lgkmcnt(0)
	v_mfma_f32_16x16x32_bf16 v[62:65], v[130:133], v[186:189], v[62:65]
	v_mfma_f32_16x16x32_bf16 v[62:65], v[134:137], v[198:201], v[62:65]
	v_mfma_f32_16x16x32_bf16 v[46:49], v[130:133], v[202:205], v[46:49]
	v_mfma_f32_16x16x32_bf16 v[46:49], v[134:137], v[206:209], v[46:49]
	v_mfma_f32_16x16x32_bf16 v[30:33], v[130:133], v[224:227], v[30:33]
	v_mfma_f32_16x16x32_bf16 v[30:33], v[134:137], v[228:231], v[30:33]
	v_mfma_f32_16x16x32_bf16 v[14:17], v[130:133], v[232:235], v[14:17]
	v_mfma_f32_16x16x32_bf16 v[14:17], v[134:137], v[236:239], v[14:17]
	v_mfma_f32_16x16x32_bf16 v[10:13], v[138:141], v[232:235], v[10:13]
	v_mfma_f32_16x16x32_bf16 v[10:13], v[142:145], v[236:239], v[10:13]
	v_mfma_f32_16x16x32_bf16 v[26:29], v[138:141], v[224:227], v[26:29]
	v_mfma_f32_16x16x32_bf16 v[26:29], v[142:145], v[228:231], v[26:29]
	v_mfma_f32_16x16x32_bf16 v[42:45], v[138:141], v[202:205], v[42:45]
	v_mfma_f32_16x16x32_bf16 v[42:45], v[142:145], v[206:209], v[42:45]
	v_mfma_f32_16x16x32_bf16 v[58:61], v[138:141], v[186:189], v[58:61]
	v_mfma_f32_16x16x32_bf16 v[58:61], v[142:145], v[198:201], v[58:61]
	v_mfma_f32_16x16x32_bf16 v[54:57], v[158:161], v[186:189], v[54:57]
	v_mfma_f32_16x16x32_bf16 v[54:57], v[174:177], v[198:201], v[54:57]
	v_mfma_f32_16x16x32_bf16 v[38:41], v[158:161], v[202:205], v[38:41]
	v_mfma_f32_16x16x32_bf16 v[38:41], v[174:177], v[206:209], v[38:41]
	v_mfma_f32_16x16x32_bf16 v[22:25], v[158:161], v[224:227], v[22:25]
	v_mfma_f32_16x16x32_bf16 v[22:25], v[174:177], v[228:231], v[22:25]
	v_mfma_f32_16x16x32_bf16 v[6:9], v[158:161], v[232:235], v[6:9]
	v_mfma_f32_16x16x32_bf16 v[6:9], v[174:177], v[236:239], v[6:9]
	v_mfma_f32_16x16x32_bf16 v[2:5], v[178:181], v[232:235], v[2:5]
	v_mfma_f32_16x16x32_bf16 v[2:5], v[182:185], v[236:239], v[2:5]
	v_mfma_f32_16x16x32_bf16 v[18:21], v[178:181], v[224:227], v[18:21]
	v_mfma_f32_16x16x32_bf16 v[18:21], v[182:185], v[228:231], v[18:21]
	v_mfma_f32_16x16x32_bf16 v[34:37], v[178:181], v[202:205], v[34:37]
	v_mfma_f32_16x16x32_bf16 v[34:37], v[182:185], v[206:209], v[34:37]
	v_mfma_f32_16x16x32_bf16 v[50:53], v[178:181], v[186:189], v[50:53]
	v_mfma_f32_16x16x32_bf16 v[50:53], v[182:185], v[198:201], v[50:53]
	s_setprio 0
	s_barrier
	s_add_i32 s57, 0, 0x18000
	s_add_i32 s58, 0, 0x1c000
	v_add_u32_e32 v142, s57, v193
	v_add_u32_e32 v170, s58, v193
	ds_read_b128 v[130:133], v142
	ds_read_b128 v[134:137], v142 offset:1024
	ds_read_b128 v[138:141], v142 offset:2048
	ds_read_b128 v[142:145], v142 offset:3072
	ds_read_b128 v[158:161], v170
	ds_read_b128 v[174:177], v170 offset:1024
	ds_read_b128 v[178:181], v170 offset:2048
	ds_read_b128 v[182:185], v170 offset:3072
	s_add_u32 s20, s20, 0x80000
	s_addc_u32 s21, s21, 0
	s_mov_b32 m0, s28
	ds_read_b128 v[186:189], v196 offset:32768
	ds_read_b128 v[198:201], v196 offset:33792
	ds_read_b128 v[202:205], v196 offset:34816
	ds_read_b128 v[206:209], v196 offset:35840
	ds_read_b128 v[224:227], v196 offset:36864
	ds_read_b128 v[228:231], v196 offset:37888
	ds_read_b128 v[232:235], v196 offset:38912
	ds_read_b128 v[236:239], v196 offset:39936
	global_load_lds_dwordx4 v150, s[20:21]
	s_mov_b32 m0, s29
	s_nop 0
	global_load_lds_dwordx4 v148, s[20:21]
	s_waitcnt vmcnt(8)
	s_waitcnt lgkmcnt(0)
	s_barrier
	s_setprio 1
	s_waitcnt lgkmcnt(0)
	v_mfma_f32_16x16x32_bf16 v[126:129], v[130:133], v[186:189], v[126:129]
	v_mfma_f32_16x16x32_bf16 v[126:129], v[134:137], v[198:201], v[126:129]
	v_mfma_f32_16x16x32_bf16 v[110:113], v[130:133], v[202:205], v[110:113]
	v_mfma_f32_16x16x32_bf16 v[110:113], v[134:137], v[206:209], v[110:113]
	v_mfma_f32_16x16x32_bf16 v[94:97], v[130:133], v[224:227], v[94:97]
	v_mfma_f32_16x16x32_bf16 v[94:97], v[134:137], v[228:231], v[94:97]
	v_mfma_f32_16x16x32_bf16 v[78:81], v[130:133], v[232:235], v[78:81]
	v_mfma_f32_16x16x32_bf16 v[78:81], v[134:137], v[236:239], v[78:81]
	v_mfma_f32_16x16x32_bf16 v[74:77], v[138:141], v[232:235], v[74:77]
	v_mfma_f32_16x16x32_bf16 v[74:77], v[142:145], v[236:239], v[74:77]
	v_mfma_f32_16x16x32_bf16 v[90:93], v[138:141], v[224:227], v[90:93]
	v_mfma_f32_16x16x32_bf16 v[90:93], v[142:145], v[228:231], v[90:93]
	v_mfma_f32_16x16x32_bf16 v[106:109], v[138:141], v[202:205], v[106:109]
	v_mfma_f32_16x16x32_bf16 v[106:109], v[142:145], v[206:209], v[106:109]
	v_mfma_f32_16x16x32_bf16 v[122:125], v[138:141], v[186:189], v[122:125]
	v_mfma_f32_16x16x32_bf16 v[122:125], v[142:145], v[198:201], v[122:125]
	v_mfma_f32_16x16x32_bf16 v[118:121], v[158:161], v[186:189], v[118:121]
	v_mfma_f32_16x16x32_bf16 v[118:121], v[174:177], v[198:201], v[118:121]
	v_mfma_f32_16x16x32_bf16 v[102:105], v[158:161], v[202:205], v[102:105]
	v_mfma_f32_16x16x32_bf16 v[102:105], v[174:177], v[206:209], v[102:105]
	v_mfma_f32_16x16x32_bf16 v[86:89], v[158:161], v[224:227], v[86:89]
	v_mfma_f32_16x16x32_bf16 v[86:89], v[174:177], v[228:231], v[86:89]
	v_mfma_f32_16x16x32_bf16 v[70:73], v[158:161], v[232:235], v[70:73]
	v_mfma_f32_16x16x32_bf16 v[70:73], v[174:177], v[236:239], v[70:73]
	v_mfma_f32_16x16x32_bf16 v[66:69], v[178:181], v[232:235], v[66:69]
	v_mfma_f32_16x16x32_bf16 v[66:69], v[182:185], v[236:239], v[66:69]
	v_mfma_f32_16x16x32_bf16 v[82:85], v[178:181], v[224:227], v[82:85]
	v_mfma_f32_16x16x32_bf16 v[82:85], v[182:185], v[228:231], v[82:85]
	v_mfma_f32_16x16x32_bf16 v[98:101], v[178:181], v[202:205], v[98:101]
	v_mfma_f32_16x16x32_bf16 v[98:101], v[182:185], v[206:209], v[98:101]
	v_mfma_f32_16x16x32_bf16 v[114:117], v[178:181], v[186:189], v[114:117]
	v_mfma_f32_16x16x32_bf16 v[114:117], v[182:185], v[198:201], v[114:117]
	s_setprio 0
	s_barrier
	s_add_i32 s20, s57, s33
	v_lshl_add_u64 v[162:163], v[162:163], 0, s[30:31]
	s_mov_b32 m0, s20
	ds_read_b128 v[186:189], v196 offset:49152
	ds_read_b128 v[198:201], v196 offset:50176
	ds_read_b128 v[202:205], v196 offset:51200
	ds_read_b128 v[206:209], v196 offset:52224
	ds_read_b128 v[224:227], v196 offset:53248
	ds_read_b128 v[228:231], v196 offset:54272
	ds_read_b128 v[232:235], v196 offset:55296
	ds_read_b128 v[236:239], v196 offset:56320
	global_load_lds_dwordx4 v[162:163], off
	s_add_i32 m0, s20, 0x2000
	s_add_u32 s16, s16, 0x80080
	v_lshl_add_u64 v[162:163], v[164:165], 0, s[30:31]
	s_addc_u32 s17, s17, 0
	s_add_i32 s20, s58, s33
	global_load_lds_dwordx4 v[162:163], off
	s_mov_b32 m0, s20
	s_nop 0
	global_load_lds_dwordx4 v0, s[16:17]
	s_add_i32 m0, s20, 0x2000
	s_nop 0
	global_load_lds_dwordx4 v146, s[16:17]
	v_lshl_add_u64 v[162:163], v[166:167], 0, s[30:31]
	s_mov_b32 m0, s48
	s_nop 0
	global_load_lds_dwordx4 v[162:163], off
	v_lshl_add_u64 v[162:163], v[168:169], 0, s[30:31]
	s_mov_b32 m0, s49
	s_nop 0
	global_load_lds_dwordx4 v[162:163], off
	s_waitcnt vmcnt(8)
	s_waitcnt lgkmcnt(0)
	s_barrier
	s_setprio 1
	s_waitcnt lgkmcnt(0)
	v_mfma_f32_16x16x32_bf16 v[62:65], v[130:133], v[186:189], v[62:65]
	v_mfma_f32_16x16x32_bf16 v[62:65], v[134:137], v[198:201], v[62:65]
	v_mfma_f32_16x16x32_bf16 v[46:49], v[130:133], v[202:205], v[46:49]
	v_mfma_f32_16x16x32_bf16 v[46:49], v[134:137], v[206:209], v[46:49]
	v_mfma_f32_16x16x32_bf16 v[30:33], v[130:133], v[224:227], v[30:33]
	v_mfma_f32_16x16x32_bf16 v[30:33], v[134:137], v[228:231], v[30:33]
	v_mfma_f32_16x16x32_bf16 v[14:17], v[130:133], v[232:235], v[14:17]
	v_mfma_f32_16x16x32_bf16 v[14:17], v[134:137], v[236:239], v[14:17]
	v_mfma_f32_16x16x32_bf16 v[10:13], v[138:141], v[232:235], v[10:13]
	v_mfma_f32_16x16x32_bf16 v[10:13], v[142:145], v[236:239], v[10:13]
	v_mfma_f32_16x16x32_bf16 v[26:29], v[138:141], v[224:227], v[26:29]
	v_mfma_f32_16x16x32_bf16 v[26:29], v[142:145], v[228:231], v[26:29]
	v_mfma_f32_16x16x32_bf16 v[42:45], v[138:141], v[202:205], v[42:45]
	v_mfma_f32_16x16x32_bf16 v[42:45], v[142:145], v[206:209], v[42:45]
	v_mfma_f32_16x16x32_bf16 v[58:61], v[138:141], v[186:189], v[58:61]
	v_mfma_f32_16x16x32_bf16 v[58:61], v[142:145], v[198:201], v[58:61]
	v_mfma_f32_16x16x32_bf16 v[54:57], v[158:161], v[186:189], v[54:57]
	v_mfma_f32_16x16x32_bf16 v[54:57], v[174:177], v[198:201], v[54:57]
	v_mfma_f32_16x16x32_bf16 v[38:41], v[158:161], v[202:205], v[38:41]
	v_mfma_f32_16x16x32_bf16 v[38:41], v[174:177], v[206:209], v[38:41]
	v_mfma_f32_16x16x32_bf16 v[22:25], v[158:161], v[224:227], v[22:25]
	v_mfma_f32_16x16x32_bf16 v[22:25], v[174:177], v[228:231], v[22:25]
	v_mfma_f32_16x16x32_bf16 v[6:9], v[158:161], v[232:235], v[6:9]
	v_mfma_f32_16x16x32_bf16 v[6:9], v[174:177], v[236:239], v[6:9]
	v_mfma_f32_16x16x32_bf16 v[2:5], v[178:181], v[232:235], v[2:5]
	v_mfma_f32_16x16x32_bf16 v[2:5], v[182:185], v[236:239], v[2:5]
	v_mfma_f32_16x16x32_bf16 v[18:21], v[178:181], v[224:227], v[18:21]
	v_mfma_f32_16x16x32_bf16 v[18:21], v[182:185], v[228:231], v[18:21]
	v_mfma_f32_16x16x32_bf16 v[34:37], v[178:181], v[202:205], v[34:37]
	v_mfma_f32_16x16x32_bf16 v[34:37], v[182:185], v[206:209], v[34:37]
	v_mfma_f32_16x16x32_bf16 v[50:53], v[178:181], v[186:189], v[50:53]
	v_mfma_f32_16x16x32_bf16 v[50:53], v[182:185], v[198:201], v[50:53]
	s_setprio 0
	s_barrier
	s_add_i32 s56, s56, 2
	s_add_u32 s6, s6, 0x100
	s_addc_u32 s7, s7, 0
	s_add_u32 s54, s54, 0x100
	s_addc_u32 s55, s55, 0
	s_cmp_gt_u32 s56, 29
	s_cbranch_scc0 .LBB0_665
	v_readlane_b32 s6, v253, 2
	v_readlane_b32 s7, v253, 3
	s_and_b64 vcc, exec, s[6:7]
	s_cbranch_vccz .LBB0_670
	s_barrier
	s_cmp_lt_i32 s51, 22
	s_mov_b64 s[6:7], -1
	s_cbranch_scc1 .LBB0_671

.LBB0_1913:
	s_add_i32 s52, s20, 2
	s_add_u32 s14, s16, 0xfff80080
	s_addc_u32 s15, s17, -1
	s_add_i32 s53, 0, 0x10000
	s_cmp_eq_u32 s49, s20
	s_cselect_b32 s21, s7, s15
	s_cselect_b32 s20, s6, s14
	v_add_u32_e32 v0, s53, v189
	s_cselect_b32 s15, s13, s51
	s_cselect_b32 s14, s12, s50
	s_add_i32 s56, 0, 0x14000
	ds_read_b128 v[132:135], v0
	ds_read_b128 v[148:151], v0 offset:1024
	ds_read_b128 v[152:155], v0 offset:2048
	ds_read_b128 v[156:159], v0 offset:3072
	v_add_u32_e32 v0, s56, v189
	ds_read_b128 v[160:163], v0
	ds_read_b128 v[164:167], v0 offset:1024
	ds_read_b128 v[168:171], v0 offset:2048
	ds_read_b128 v[172:175], v0 offset:3072
	s_add_i32 m0, s26, 0xc000
	ds_read_b128 v[176:179], v191
	ds_read_b128 v[180:183], v191 offset:1024
	ds_read_b128 v[184:187], v191 offset:2048
	ds_read_b128 v[192:195], v191 offset:3072
	ds_read_b128 v[196:199], v191 offset:4096
	ds_read_b128 v[200:203], v191 offset:5120
	ds_read_b128 v[204:207], v191 offset:6144
	ds_read_b128 v[208:211], v191 offset:7168
	global_load_lds_dwordx4 v144, s[16:17]
	s_add_i32 m0, s26, 0xe000
	s_nop 0
	global_load_lds_dwordx4 v146, s[16:17]
	s_waitcnt vmcnt(8)
	s_waitcnt lgkmcnt(0)
	s_barrier
	s_setprio 1
	s_waitcnt lgkmcnt(0)
	v_mfma_f32_16x16x32_bf16 v[128:131], v[132:135], v[176:179], v[128:131]
	v_mfma_f32_16x16x32_bf16 v[128:131], v[148:151], v[180:183], v[128:131]
	v_mfma_f32_16x16x32_bf16 v[120:123], v[132:135], v[184:187], v[120:123]
	v_mfma_f32_16x16x32_bf16 v[120:123], v[148:151], v[192:195], v[120:123]
	v_mfma_f32_16x16x32_bf16 v[112:115], v[132:135], v[196:199], v[112:115]
	v_mfma_f32_16x16x32_bf16 v[112:115], v[148:151], v[200:203], v[112:115]
	v_mfma_f32_16x16x32_bf16 v[104:107], v[132:135], v[204:207], v[104:107]
	v_mfma_f32_16x16x32_bf16 v[104:107], v[148:151], v[208:211], v[104:107]
	v_mfma_f32_16x16x32_bf16 v[100:103], v[152:155], v[204:207], v[100:103]
	v_mfma_f32_16x16x32_bf16 v[100:103], v[156:159], v[208:211], v[100:103]
	v_mfma_f32_16x16x32_bf16 v[108:111], v[152:155], v[196:199], v[108:111]
	v_mfma_f32_16x16x32_bf16 v[108:111], v[156:159], v[200:203], v[108:111]
	v_mfma_f32_16x16x32_bf16 v[116:119], v[152:155], v[184:187], v[116:119]
	v_mfma_f32_16x16x32_bf16 v[116:119], v[156:159], v[192:195], v[116:119]
	v_mfma_f32_16x16x32_bf16 v[124:127], v[152:155], v[176:179], v[124:127]
	v_mfma_f32_16x16x32_bf16 v[124:127], v[156:159], v[180:183], v[124:127]
	v_mfma_f32_16x16x32_bf16 v[96:99], v[160:163], v[176:179], v[96:99]
	v_mfma_f32_16x16x32_bf16 v[96:99], v[164:167], v[180:183], v[96:99]
	v_mfma_f32_16x16x32_bf16 v[88:91], v[160:163], v[184:187], v[88:91]
	v_mfma_f32_16x16x32_bf16 v[88:91], v[164:167], v[192:195], v[88:91]
	v_mfma_f32_16x16x32_bf16 v[80:83], v[160:163], v[196:199], v[80:83]
	v_mfma_f32_16x16x32_bf16 v[80:83], v[164:167], v[200:203], v[80:83]
	v_mfma_f32_16x16x32_bf16 v[72:75], v[160:163], v[204:207], v[72:75]
	v_mfma_f32_16x16x32_bf16 v[72:75], v[164:167], v[208:211], v[72:75]
	v_mfma_f32_16x16x32_bf16 v[68:71], v[168:171], v[204:207], v[68:71]
	v_mfma_f32_16x16x32_bf16 v[68:71], v[172:175], v[208:211], v[68:71]
	v_mfma_f32_16x16x32_bf16 v[76:79], v[168:171], v[196:199], v[76:79]
	v_mfma_f32_16x16x32_bf16 v[76:79], v[172:175], v[200:203], v[76:79]
	v_mfma_f32_16x16x32_bf16 v[84:87], v[168:171], v[184:187], v[84:87]
	v_mfma_f32_16x16x32_bf16 v[84:87], v[172:175], v[192:195], v[84:87]
	v_mfma_f32_16x16x32_bf16 v[92:95], v[168:171], v[176:179], v[92:95]
	v_mfma_f32_16x16x32_bf16 v[92:95], v[172:175], v[180:183], v[92:95]
	s_setprio 0
	s_barrier
	s_add_i32 s53, s53, s33
	v_lshl_add_u64 v[212:213], s[14:15], 0, v[140:141]
	s_mov_b32 m0, s53
	ds_read_b128 v[176:179], v191 offset:16384
	ds_read_b128 v[180:183], v191 offset:17408
	ds_read_b128 v[184:187], v191 offset:18432
	ds_read_b128 v[192:195], v191 offset:19456
	ds_read_b128 v[196:199], v191 offset:20480
	ds_read_b128 v[200:203], v191 offset:21504
	ds_read_b128 v[204:207], v191 offset:22528
	ds_read_b128 v[208:211], v191 offset:23552
	global_load_lds_dwordx4 v[212:213], off
	s_add_i32 m0, s53, 0x2000
	s_add_u32 s54, s14, 0x80000
	v_lshl_add_u64 v[220:221], s[14:15], 0, v[136:137]
	s_addc_u32 s55, s15, 0
	s_add_i32 s53, s56, s33
	global_load_lds_dwordx4 v[220:221], off
	s_mov_b32 m0, s53
	v_lshl_add_u64 v[224:225], s[20:21], 0, v[142:143]
	global_load_lds_dwordx4 v140, s[54:55]
	s_add_i32 m0, s53, 0x2000
	v_lshl_add_u64 v[226:227], s[20:21], 0, v[138:139]
	global_load_lds_dwordx4 v136, s[54:55]
	s_mov_b32 m0, s26
	s_nop 0
	global_load_lds_dwordx4 v[224:225], off
	s_mov_b32 m0, s27
	s_nop 0
	global_load_lds_dwordx4 v[226:227], off
	s_waitcnt vmcnt(8)
	s_waitcnt lgkmcnt(0)
	s_barrier
	s_setprio 1
	s_waitcnt lgkmcnt(0)
	v_mfma_f32_16x16x32_bf16 v[64:67], v[132:135], v[176:179], v[64:67]
	v_mfma_f32_16x16x32_bf16 v[64:67], v[148:151], v[180:183], v[64:67]
	v_mfma_f32_16x16x32_bf16 v[56:59], v[132:135], v[184:187], v[56:59]
	v_mfma_f32_16x16x32_bf16 v[56:59], v[148:151], v[192:195], v[56:59]
	v_mfma_f32_16x16x32_bf16 v[48:51], v[132:135], v[196:199], v[48:51]
	v_mfma_f32_16x16x32_bf16 v[48:51], v[148:151], v[200:203], v[48:51]
	v_mfma_f32_16x16x32_bf16 v[40:43], v[132:135], v[204:207], v[40:43]
	v_mfma_f32_16x16x32_bf16 v[40:43], v[148:151], v[208:211], v[40:43]
	v_mfma_f32_16x16x32_bf16 v[36:39], v[152:155], v[204:207], v[36:39]
	v_mfma_f32_16x16x32_bf16 v[36:39], v[156:159], v[208:211], v[36:39]
	v_mfma_f32_16x16x32_bf16 v[44:47], v[152:155], v[196:199], v[44:47]
	v_mfma_f32_16x16x32_bf16 v[44:47], v[156:159], v[200:203], v[44:47]
	v_mfma_f32_16x16x32_bf16 v[52:55], v[152:155], v[184:187], v[52:55]
	v_mfma_f32_16x16x32_bf16 v[52:55], v[156:159], v[192:195], v[52:55]
	v_mfma_f32_16x16x32_bf16 v[60:63], v[152:155], v[176:179], v[60:63]
	v_mfma_f32_16x16x32_bf16 v[60:63], v[156:159], v[180:183], v[60:63]
	v_mfma_f32_16x16x32_bf16 v[32:35], v[160:163], v[176:179], v[32:35]
	v_mfma_f32_16x16x32_bf16 v[32:35], v[164:167], v[180:183], v[32:35]
	v_mfma_f32_16x16x32_bf16 v[24:27], v[160:163], v[184:187], v[24:27]
	v_mfma_f32_16x16x32_bf16 v[24:27], v[164:167], v[192:195], v[24:27]
	v_mfma_f32_16x16x32_bf16 v[16:19], v[160:163], v[196:199], v[16:19]
	v_mfma_f32_16x16x32_bf16 v[16:19], v[164:167], v[200:203], v[16:19]
	v_mfma_f32_16x16x32_bf16 v[8:11], v[160:163], v[204:207], v[8:11]
	v_mfma_f32_16x16x32_bf16 v[8:11], v[164:167], v[208:211], v[8:11]
	v_mfma_f32_16x16x32_bf16 v[2:5], v[168:171], v[204:207], v[4:7]
	v_mfma_f32_16x16x32_bf16 v[2:5], v[172:175], v[208:211], v[2:5]
	v_mfma_f32_16x16x32_bf16 v[12:15], v[168:171], v[196:199], v[12:15]
	v_mfma_f32_16x16x32_bf16 v[12:15], v[172:175], v[200:203], v[12:15]
	v_mfma_f32_16x16x32_bf16 v[20:23], v[168:171], v[184:187], v[20:23]
	v_mfma_f32_16x16x32_bf16 v[20:23], v[172:175], v[192:195], v[20:23]
	v_mfma_f32_16x16x32_bf16 v[28:31], v[168:171], v[176:179], v[28:31]
	v_mfma_f32_16x16x32_bf16 v[28:31], v[172:175], v[180:183], v[28:31]
	s_setprio 0
	s_barrier
	s_add_i32 s53, 0, 0x18000
	v_add_u32_e32 v0, s53, v189
	s_add_i32 s54, 0, 0x1c000
	ds_read_b128 v[132:135], v0
	ds_read_b128 v[148:151], v0 offset:1024
	ds_read_b128 v[152:155], v0 offset:2048
	ds_read_b128 v[156:159], v0 offset:3072
	v_add_u32_e32 v0, s54, v189
	ds_read_b128 v[160:163], v0
	ds_read_b128 v[164:167], v0 offset:1024
	ds_read_b128 v[168:171], v0 offset:2048
	ds_read_b128 v[172:175], v0 offset:3072
	s_add_u32 s20, s20, 0x80000
	s_addc_u32 s21, s21, 0
	s_mov_b32 m0, s28
	ds_read_b128 v[176:179], v191 offset:32768
	ds_read_b128 v[180:183], v191 offset:33792
	ds_read_b128 v[184:187], v191 offset:34816
	ds_read_b128 v[192:195], v191 offset:35840
	ds_read_b128 v[196:199], v191 offset:36864
	ds_read_b128 v[200:203], v191 offset:37888
	ds_read_b128 v[204:207], v191 offset:38912
	ds_read_b128 v[208:211], v191 offset:39936
	global_load_lds_dwordx4 v142, s[20:21]
	s_mov_b32 m0, s29
	s_nop 0
	global_load_lds_dwordx4 v138, s[20:21]
	s_waitcnt vmcnt(8)
	s_waitcnt lgkmcnt(0)
	s_barrier
	s_setprio 1
	s_waitcnt lgkmcnt(0)
	v_mfma_f32_16x16x32_bf16 v[128:131], v[132:135], v[176:179], v[128:131]
	v_mfma_f32_16x16x32_bf16 v[128:131], v[148:151], v[180:183], v[128:131]
	v_mfma_f32_16x16x32_bf16 v[120:123], v[132:135], v[184:187], v[120:123]
	v_mfma_f32_16x16x32_bf16 v[120:123], v[148:151], v[192:195], v[120:123]
	v_mfma_f32_16x16x32_bf16 v[112:115], v[132:135], v[196:199], v[112:115]
	v_mfma_f32_16x16x32_bf16 v[112:115], v[148:151], v[200:203], v[112:115]
	v_mfma_f32_16x16x32_bf16 v[104:107], v[132:135], v[204:207], v[104:107]
	v_mfma_f32_16x16x32_bf16 v[104:107], v[148:151], v[208:211], v[104:107]
	v_mfma_f32_16x16x32_bf16 v[100:103], v[152:155], v[204:207], v[100:103]
	v_mfma_f32_16x16x32_bf16 v[100:103], v[156:159], v[208:211], v[100:103]
	v_mfma_f32_16x16x32_bf16 v[108:111], v[152:155], v[196:199], v[108:111]
	v_mfma_f32_16x16x32_bf16 v[108:111], v[156:159], v[200:203], v[108:111]
	v_mfma_f32_16x16x32_bf16 v[116:119], v[152:155], v[184:187], v[116:119]
	v_mfma_f32_16x16x32_bf16 v[116:119], v[156:159], v[192:195], v[116:119]
	v_mfma_f32_16x16x32_bf16 v[124:127], v[152:155], v[176:179], v[124:127]
	v_mfma_f32_16x16x32_bf16 v[124:127], v[156:159], v[180:183], v[124:127]
	v_mfma_f32_16x16x32_bf16 v[96:99], v[160:163], v[176:179], v[96:99]
	v_mfma_f32_16x16x32_bf16 v[96:99], v[164:167], v[180:183], v[96:99]
	v_mfma_f32_16x16x32_bf16 v[88:91], v[160:163], v[184:187], v[88:91]
	v_mfma_f32_16x16x32_bf16 v[88:91], v[164:167], v[192:195], v[88:91]
	v_mfma_f32_16x16x32_bf16 v[80:83], v[160:163], v[196:199], v[80:83]
	v_mfma_f32_16x16x32_bf16 v[80:83], v[164:167], v[200:203], v[80:83]
	v_mfma_f32_16x16x32_bf16 v[72:75], v[160:163], v[204:207], v[72:75]
	v_mfma_f32_16x16x32_bf16 v[72:75], v[164:167], v[208:211], v[72:75]
	v_mfma_f32_16x16x32_bf16 v[68:71], v[168:171], v[204:207], v[68:71]
	v_mfma_f32_16x16x32_bf16 v[68:71], v[172:175], v[208:211], v[68:71]
	v_mfma_f32_16x16x32_bf16 v[76:79], v[168:171], v[196:199], v[76:79]
	v_mfma_f32_16x16x32_bf16 v[76:79], v[172:175], v[200:203], v[76:79]
	v_mfma_f32_16x16x32_bf16 v[84:87], v[168:171], v[184:187], v[84:87]
	v_mfma_f32_16x16x32_bf16 v[84:87], v[172:175], v[192:195], v[84:87]
	v_mfma_f32_16x16x32_bf16 v[92:95], v[168:171], v[176:179], v[92:95]
	v_mfma_f32_16x16x32_bf16 v[92:95], v[172:175], v[180:183], v[92:95]
	s_setprio 0
	s_barrier
	s_add_i32 s20, s53, s33
	v_lshl_add_u64 v[6:7], v[212:213], 0, s[30:31]
	s_mov_b32 m0, s20
	ds_read_b128 v[176:179], v191 offset:49152
	ds_read_b128 v[180:183], v191 offset:50176
	ds_read_b128 v[184:187], v191 offset:51200
	ds_read_b128 v[192:195], v191 offset:52224
	ds_read_b128 v[196:199], v191 offset:53248
	ds_read_b128 v[200:203], v191 offset:54272
	ds_read_b128 v[204:207], v191 offset:55296
	ds_read_b128 v[208:211], v191 offset:56320
	global_load_lds_dwordx4 v[6:7], off
	s_add_i32 m0, s20, 0x2000
	s_add_u32 s14, s14, 0x80080
	v_lshl_add_u64 v[6:7], v[220:221], 0, s[30:31]
	s_addc_u32 s15, s15, 0
	s_add_i32 s20, s54, s33
	global_load_lds_dwordx4 v[6:7], off
	s_mov_b32 m0, s20
	s_nop 0
	global_load_lds_dwordx4 v140, s[14:15]
	s_add_i32 m0, s20, 0x2000
	s_nop 0
	global_load_lds_dwordx4 v136, s[14:15]
	v_lshl_add_u64 v[6:7], v[224:225], 0, s[30:31]
	s_mov_b32 m0, s34
	s_nop 0
	global_load_lds_dwordx4 v[6:7], off
	v_lshl_add_u64 v[6:7], v[226:227], 0, s[30:31]
	s_mov_b32 m0, s35
	s_nop 0
	global_load_lds_dwordx4 v[6:7], off
	s_waitcnt vmcnt(8)
	s_waitcnt lgkmcnt(0)
	s_barrier
	s_setprio 1
	s_waitcnt lgkmcnt(0)
	v_mfma_f32_16x16x32_bf16 v[64:67], v[132:135], v[176:179], v[64:67]
	v_mfma_f32_16x16x32_bf16 v[64:67], v[148:151], v[180:183], v[64:67]
	v_mfma_f32_16x16x32_bf16 v[56:59], v[132:135], v[184:187], v[56:59]
	v_mfma_f32_16x16x32_bf16 v[56:59], v[148:151], v[192:195], v[56:59]
	v_mfma_f32_16x16x32_bf16 v[48:51], v[132:135], v[196:199], v[48:51]
	v_mfma_f32_16x16x32_bf16 v[48:51], v[148:151], v[200:203], v[48:51]
	v_mfma_f32_16x16x32_bf16 v[40:43], v[132:135], v[204:207], v[40:43]
	v_mfma_f32_16x16x32_bf16 v[40:43], v[148:151], v[208:211], v[40:43]
	v_mfma_f32_16x16x32_bf16 v[36:39], v[152:155], v[204:207], v[36:39]
	v_mfma_f32_16x16x32_bf16 v[36:39], v[156:159], v[208:211], v[36:39]
	v_mfma_f32_16x16x32_bf16 v[44:47], v[152:155], v[196:199], v[44:47]
	v_mfma_f32_16x16x32_bf16 v[44:47], v[156:159], v[200:203], v[44:47]
	v_mfma_f32_16x16x32_bf16 v[52:55], v[152:155], v[184:187], v[52:55]
	v_mfma_f32_16x16x32_bf16 v[52:55], v[156:159], v[192:195], v[52:55]
	v_mfma_f32_16x16x32_bf16 v[60:63], v[152:155], v[176:179], v[60:63]
	v_mfma_f32_16x16x32_bf16 v[60:63], v[156:159], v[180:183], v[60:63]
	v_mfma_f32_16x16x32_bf16 v[32:35], v[160:163], v[176:179], v[32:35]
	v_mfma_f32_16x16x32_bf16 v[32:35], v[164:167], v[180:183], v[32:35]
	v_mfma_f32_16x16x32_bf16 v[24:27], v[160:163], v[184:187], v[24:27]
	v_mfma_f32_16x16x32_bf16 v[24:27], v[164:167], v[192:195], v[24:27]
	v_mfma_f32_16x16x32_bf16 v[16:19], v[160:163], v[196:199], v[16:19]
	v_mfma_f32_16x16x32_bf16 v[16:19], v[164:167], v[200:203], v[16:19]
	v_mfma_f32_16x16x32_bf16 v[6:9], v[160:163], v[204:207], v[8:11]
	v_mfma_f32_16x16x32_bf16 v[8:11], v[164:167], v[208:211], v[6:9]
	v_mfma_f32_16x16x32_bf16 v[2:5], v[168:171], v[204:207], v[2:5]
	v_mfma_f32_16x16x32_bf16 v[4:7], v[172:175], v[208:211], v[2:5]
	v_mfma_f32_16x16x32_bf16 v[12:15], v[168:171], v[196:199], v[12:15]
	v_mfma_f32_16x16x32_bf16 v[12:15], v[172:175], v[200:203], v[12:15]
	v_mfma_f32_16x16x32_bf16 v[20:23], v[168:171], v[184:187], v[20:23]
	v_mfma_f32_16x16x32_bf16 v[20:23], v[172:175], v[192:195], v[20:23]
	v_mfma_f32_16x16x32_bf16 v[28:31], v[168:171], v[176:179], v[28:31]
	v_mfma_f32_16x16x32_bf16 v[28:31], v[172:175], v[180:183], v[28:31]
	s_setprio 0
	s_barrier
	s_add_u32 s16, s16, 0x100
	s_addc_u32 s17, s17, 0
	s_add_u32 s50, s50, 0x100
	s_addc_u32 s51, s51, 0
	s_cmp_ge_u32 s52, s11
	s_mov_b32 s20, s52
	s_cbranch_scc0 .LBB0_1913
	v_readlane_b32 s14, v253, 2
	v_readlane_b32 s15, v253, 3
	s_and_b64 vcc, exec, s[14:15]
	s_cbranch_vccz .LBB0_1916
	s_barrier

.LBB0_1997:
	s_add_u32 s22, s16, 0xfff80080
	s_addc_u32 s23, s17, -1
	s_add_i32 s69, 0, 0x10000
	s_cmp_eq_u32 s25, 28
	s_cselect_b32 s27, s11, s23
	s_cselect_b32 s26, s18, s22
	s_cselect_b32 s23, s9, s24
	s_cselect_b32 s22, s19, s21
	s_add_i32 s72, 0, 0x14000
	v_add_u32_e32 v142, s69, v205
	v_add_u32_e32 v162, s72, v205
	ds_read_b128 v[130:133], v142
	ds_read_b128 v[134:137], v142 offset:1024
	ds_read_b128 v[138:141], v142 offset:2048
	ds_read_b128 v[142:145], v142 offset:3072
	ds_read_b128 v[146:149], v162
	ds_read_b128 v[150:153], v162 offset:1024
	ds_read_b128 v[154:157], v162 offset:2048
	ds_read_b128 v[162:165], v162 offset:3072
	s_add_i32 m0, s54, 0xc000
	ds_read_b128 v[166:169], v230
	ds_read_b128 v[170:173], v230 offset:1024
	ds_read_b128 v[184:187], v230 offset:2048
	ds_read_b128 v[188:191], v230 offset:3072
	ds_read_b128 v[192:195], v230 offset:4096
	ds_read_b128 v[196:199], v230 offset:5120
	ds_read_b128 v[200:203], v230 offset:6144
	ds_read_b128 v[232:235], v230 offset:7168
	global_load_lds_dwordx4 v180, s[16:17]
	s_add_i32 m0, s54, 0xe000
	s_nop 0
	global_load_lds_dwordx4 v182, s[16:17]
	s_waitcnt vmcnt(8)
	s_waitcnt lgkmcnt(0)
	s_barrier
	s_setprio 1
	s_waitcnt lgkmcnt(0)
	v_mfma_f32_16x16x32_bf16 v[126:129], v[130:133], v[166:169], v[126:129]
	v_mfma_f32_16x16x32_bf16 v[126:129], v[134:137], v[170:173], v[126:129]
	v_mfma_f32_16x16x32_bf16 v[118:121], v[130:133], v[184:187], v[118:121]
	v_mfma_f32_16x16x32_bf16 v[118:121], v[134:137], v[188:191], v[118:121]
	v_mfma_f32_16x16x32_bf16 v[110:113], v[130:133], v[192:195], v[110:113]
	v_mfma_f32_16x16x32_bf16 v[110:113], v[134:137], v[196:199], v[110:113]
	v_mfma_f32_16x16x32_bf16 v[102:105], v[130:133], v[200:203], v[102:105]
	v_mfma_f32_16x16x32_bf16 v[102:105], v[134:137], v[232:235], v[102:105]
	v_mfma_f32_16x16x32_bf16 v[38:41], v[138:141], v[200:203], v[38:41]
	v_mfma_f32_16x16x32_bf16 v[38:41], v[142:145], v[232:235], v[38:41]
	v_mfma_f32_16x16x32_bf16 v[66:69], v[138:141], v[192:195], v[66:69]
	v_mfma_f32_16x16x32_bf16 v[66:69], v[142:145], v[196:199], v[66:69]
	v_mfma_f32_16x16x32_bf16 v[86:89], v[138:141], v[184:187], v[86:89]
	v_mfma_f32_16x16x32_bf16 v[86:89], v[142:145], v[188:191], v[86:89]
	v_mfma_f32_16x16x32_bf16 v[74:77], v[138:141], v[166:169], v[74:77]
	v_mfma_f32_16x16x32_bf16 v[74:77], v[142:145], v[170:173], v[74:77]
	v_mfma_f32_16x16x32_bf16 v[122:125], v[146:149], v[166:169], v[122:125]
	v_mfma_f32_16x16x32_bf16 v[122:125], v[150:153], v[170:173], v[122:125]
	v_mfma_f32_16x16x32_bf16 v[114:117], v[146:149], v[184:187], v[114:117]
	v_mfma_f32_16x16x32_bf16 v[114:117], v[150:153], v[188:191], v[114:117]
	v_mfma_f32_16x16x32_bf16 v[106:109], v[146:149], v[192:195], v[106:109]
	v_mfma_f32_16x16x32_bf16 v[106:109], v[150:153], v[196:199], v[106:109]
	v_mfma_f32_16x16x32_bf16 v[98:101], v[146:149], v[200:203], v[98:101]
	v_mfma_f32_16x16x32_bf16 v[98:101], v[150:153], v[232:235], v[98:101]
	v_mfma_f32_16x16x32_bf16 v[42:45], v[154:157], v[200:203], v[42:45]
	v_mfma_f32_16x16x32_bf16 v[42:45], v[162:165], v[232:235], v[42:45]
	v_mfma_f32_16x16x32_bf16 v[70:73], v[154:157], v[192:195], v[70:73]
	v_mfma_f32_16x16x32_bf16 v[70:73], v[162:165], v[196:199], v[70:73]
	v_mfma_f32_16x16x32_bf16 v[90:93], v[154:157], v[184:187], v[90:93]
	v_mfma_f32_16x16x32_bf16 v[90:93], v[162:165], v[188:191], v[90:93]
	v_mfma_f32_16x16x32_bf16 v[82:85], v[154:157], v[166:169], v[82:85]
	v_mfma_f32_16x16x32_bf16 v[82:85], v[162:165], v[170:173], v[82:85]
	s_setprio 0
	s_barrier
	s_add_i32 s69, s69, s33
	v_lshl_add_u64 v[212:213], s[22:23], 0, v[0:1]
	s_mov_b32 m0, s69
	ds_read_b128 v[166:169], v230 offset:16384
	ds_read_b128 v[170:173], v230 offset:17408
	ds_read_b128 v[184:187], v230 offset:18432
	ds_read_b128 v[188:191], v230 offset:19456
	ds_read_b128 v[192:195], v230 offset:20480
	ds_read_b128 v[196:199], v230 offset:21504
	ds_read_b128 v[200:203], v230 offset:22528
	ds_read_b128 v[232:235], v230 offset:23552
	global_load_lds_dwordx4 v[212:213], off
	s_add_i32 m0, s69, 0x2000
	s_add_u32 s70, s22, 0x80000
	v_lshl_add_u64 v[220:221], s[22:23], 0, v[158:159]
	s_addc_u32 s71, s23, 0
	s_add_i32 s69, s72, s33
	global_load_lds_dwordx4 v[220:221], off
	s_mov_b32 m0, s69
	v_lshl_add_u64 v[238:239], s[26:27], 0, v[160:161]
	global_load_lds_dwordx4 v0, s[70:71]
	s_add_i32 m0, s69, 0x2000
	s_nop 0
	global_load_lds_dwordx4 v158, s[70:71]
	v_lshl_add_u64 v[236:237], s[26:27], 0, v[174:175]
	s_mov_b32 m0, s54
	s_nop 0
	global_load_lds_dwordx4 v[236:237], off
	s_mov_b32 m0, s55
	s_nop 0
	global_load_lds_dwordx4 v[238:239], off
	s_waitcnt vmcnt(8)
	s_waitcnt lgkmcnt(0)
	s_barrier
	s_setprio 1
	s_waitcnt lgkmcnt(0)
	v_mfma_f32_16x16x32_bf16 v[94:97], v[130:133], v[166:169], v[94:97]
	v_mfma_f32_16x16x32_bf16 v[94:97], v[134:137], v[170:173], v[94:97]
	v_mfma_f32_16x16x32_bf16 v[62:65], v[130:133], v[184:187], v[62:65]
	v_mfma_f32_16x16x32_bf16 v[62:65], v[134:137], v[188:191], v[62:65]
	v_mfma_f32_16x16x32_bf16 v[46:49], v[130:133], v[192:195], v[46:49]
	v_mfma_f32_16x16x32_bf16 v[46:49], v[134:137], v[196:199], v[46:49]
	v_mfma_f32_16x16x32_bf16 v[22:25], v[130:133], v[200:203], v[22:25]
	v_mfma_f32_16x16x32_bf16 v[22:25], v[134:137], v[232:235], v[22:25]
	v_mfma_f32_16x16x32_bf16 v[2:5], v[138:141], v[200:203], v[2:5]
	v_mfma_f32_16x16x32_bf16 v[2:5], v[142:145], v[232:235], v[2:5]
	v_mfma_f32_16x16x32_bf16 v[10:13], v[138:141], v[192:195], v[10:13]
	v_mfma_f32_16x16x32_bf16 v[10:13], v[142:145], v[196:199], v[10:13]
	v_mfma_f32_16x16x32_bf16 v[30:33], v[138:141], v[184:187], v[30:33]
	v_mfma_f32_16x16x32_bf16 v[30:33], v[142:145], v[188:191], v[30:33]
	v_mfma_f32_16x16x32_bf16 v[50:53], v[138:141], v[166:169], v[50:53]
	v_mfma_f32_16x16x32_bf16 v[50:53], v[142:145], v[170:173], v[50:53]
	v_mfma_f32_16x16x32_bf16 v[78:81], v[146:149], v[166:169], v[78:81]
	v_mfma_f32_16x16x32_bf16 v[78:81], v[150:153], v[170:173], v[78:81]
	v_mfma_f32_16x16x32_bf16 v[54:57], v[146:149], v[184:187], v[54:57]
	v_mfma_f32_16x16x32_bf16 v[54:57], v[150:153], v[188:191], v[54:57]
	v_mfma_f32_16x16x32_bf16 v[26:29], v[146:149], v[192:195], v[26:29]
	v_mfma_f32_16x16x32_bf16 v[26:29], v[150:153], v[196:199], v[26:29]
	v_mfma_f32_16x16x32_bf16 v[18:21], v[146:149], v[200:203], v[18:21]
	v_mfma_f32_16x16x32_bf16 v[18:21], v[150:153], v[232:235], v[18:21]
	v_mfma_f32_16x16x32_bf16 v[6:9], v[154:157], v[200:203], v[6:9]
	v_mfma_f32_16x16x32_bf16 v[6:9], v[162:165], v[232:235], v[6:9]
	v_mfma_f32_16x16x32_bf16 v[14:17], v[154:157], v[192:195], v[14:17]
	v_mfma_f32_16x16x32_bf16 v[14:17], v[162:165], v[196:199], v[14:17]
	v_mfma_f32_16x16x32_bf16 v[34:37], v[154:157], v[184:187], v[34:37]
	v_mfma_f32_16x16x32_bf16 v[34:37], v[162:165], v[188:191], v[34:37]
	v_mfma_f32_16x16x32_bf16 v[58:61], v[154:157], v[166:169], v[58:61]
	v_mfma_f32_16x16x32_bf16 v[58:61], v[162:165], v[170:173], v[58:61]
	s_setprio 0
	s_barrier
	s_add_i32 s69, 0, 0x18000
	s_add_i32 s70, 0, 0x1c000
	v_add_u32_e32 v142, s69, v205
	v_add_u32_e32 v162, s70, v205
	ds_read_b128 v[130:133], v142
	ds_read_b128 v[134:137], v142 offset:1024
	ds_read_b128 v[138:141], v142 offset:2048
	ds_read_b128 v[142:145], v142 offset:3072
	ds_read_b128 v[146:149], v162
	ds_read_b128 v[150:153], v162 offset:1024
	ds_read_b128 v[154:157], v162 offset:2048
	ds_read_b128 v[162:165], v162 offset:3072
	s_add_u32 s26, s26, 0x80000
	s_addc_u32 s27, s27, 0
	s_mov_b32 m0, s56
	ds_read_b128 v[166:169], v230 offset:32768
	ds_read_b128 v[170:173], v230 offset:33792
	ds_read_b128 v[184:187], v230 offset:34816
	ds_read_b128 v[188:191], v230 offset:35840
	ds_read_b128 v[192:195], v230 offset:36864
	ds_read_b128 v[196:199], v230 offset:37888
	ds_read_b128 v[200:203], v230 offset:38912
	ds_read_b128 v[232:235], v230 offset:39936
	global_load_lds_dwordx4 v174, s[26:27]
	s_mov_b32 m0, s57
	s_nop 0
	global_load_lds_dwordx4 v160, s[26:27]
	s_waitcnt vmcnt(8)
	s_waitcnt lgkmcnt(0)
	s_barrier
	s_setprio 1
	s_waitcnt lgkmcnt(0)
	v_mfma_f32_16x16x32_bf16 v[126:129], v[130:133], v[166:169], v[126:129]
	v_mfma_f32_16x16x32_bf16 v[126:129], v[134:137], v[170:173], v[126:129]
	v_mfma_f32_16x16x32_bf16 v[118:121], v[130:133], v[184:187], v[118:121]
	v_mfma_f32_16x16x32_bf16 v[118:121], v[134:137], v[188:191], v[118:121]
	v_mfma_f32_16x16x32_bf16 v[110:113], v[130:133], v[192:195], v[110:113]
	v_mfma_f32_16x16x32_bf16 v[110:113], v[134:137], v[196:199], v[110:113]
	v_mfma_f32_16x16x32_bf16 v[102:105], v[130:133], v[200:203], v[102:105]
	v_mfma_f32_16x16x32_bf16 v[102:105], v[134:137], v[232:235], v[102:105]
	v_mfma_f32_16x16x32_bf16 v[38:41], v[138:141], v[200:203], v[38:41]
	v_mfma_f32_16x16x32_bf16 v[38:41], v[142:145], v[232:235], v[38:41]
	v_mfma_f32_16x16x32_bf16 v[66:69], v[138:141], v[192:195], v[66:69]
	v_mfma_f32_16x16x32_bf16 v[66:69], v[142:145], v[196:199], v[66:69]
	v_mfma_f32_16x16x32_bf16 v[86:89], v[138:141], v[184:187], v[86:89]
	v_mfma_f32_16x16x32_bf16 v[86:89], v[142:145], v[188:191], v[86:89]
	v_mfma_f32_16x16x32_bf16 v[74:77], v[138:141], v[166:169], v[74:77]
	v_mfma_f32_16x16x32_bf16 v[74:77], v[142:145], v[170:173], v[74:77]
	v_mfma_f32_16x16x32_bf16 v[122:125], v[146:149], v[166:169], v[122:125]
	v_mfma_f32_16x16x32_bf16 v[122:125], v[150:153], v[170:173], v[122:125]
	v_mfma_f32_16x16x32_bf16 v[114:117], v[146:149], v[184:187], v[114:117]
	v_mfma_f32_16x16x32_bf16 v[114:117], v[150:153], v[188:191], v[114:117]
	v_mfma_f32_16x16x32_bf16 v[106:109], v[146:149], v[192:195], v[106:109]
	v_mfma_f32_16x16x32_bf16 v[106:109], v[150:153], v[196:199], v[106:109]
	v_mfma_f32_16x16x32_bf16 v[98:101], v[146:149], v[200:203], v[98:101]
	v_mfma_f32_16x16x32_bf16 v[98:101], v[150:153], v[232:235], v[98:101]
	v_mfma_f32_16x16x32_bf16 v[42:45], v[154:157], v[200:203], v[42:45]
	v_mfma_f32_16x16x32_bf16 v[42:45], v[162:165], v[232:235], v[42:45]
	v_mfma_f32_16x16x32_bf16 v[70:73], v[154:157], v[192:195], v[70:73]
	v_mfma_f32_16x16x32_bf16 v[70:73], v[162:165], v[196:199], v[70:73]
	v_mfma_f32_16x16x32_bf16 v[90:93], v[154:157], v[184:187], v[90:93]
	v_mfma_f32_16x16x32_bf16 v[90:93], v[162:165], v[188:191], v[90:93]
	v_mfma_f32_16x16x32_bf16 v[82:85], v[154:157], v[166:169], v[82:85]
	v_mfma_f32_16x16x32_bf16 v[82:85], v[162:165], v[170:173], v[82:85]
	s_setprio 0
	s_barrier
	s_add_i32 s26, s69, s33
	v_lshl_add_u64 v[212:213], v[212:213], 0, s[30:31]
	s_mov_b32 m0, s26
	ds_read_b128 v[166:169], v230 offset:49152
	ds_read_b128 v[170:173], v230 offset:50176
	ds_read_b128 v[184:187], v230 offset:51200
	ds_read_b128 v[188:191], v230 offset:52224
	ds_read_b128 v[192:195], v230 offset:53248
	ds_read_b128 v[196:199], v230 offset:54272
	ds_read_b128 v[200:203], v230 offset:55296
	ds_read_b128 v[232:235], v230 offset:56320
	global_load_lds_dwordx4 v[212:213], off
	s_add_i32 m0, s26, 0x2000
	s_add_u32 s22, s22, 0x80080
	v_lshl_add_u64 v[212:213], v[220:221], 0, s[30:31]
	s_addc_u32 s23, s23, 0
	s_add_i32 s26, s70, s33
	global_load_lds_dwordx4 v[212:213], off
	s_mov_b32 m0, s26
	s_nop 0
	global_load_lds_dwordx4 v0, s[22:23]
	s_add_i32 m0, s26, 0x2000
	s_nop 0
	global_load_lds_dwordx4 v158, s[22:23]
	v_lshl_add_u64 v[212:213], v[236:237], 0, s[30:31]
	s_mov_b32 m0, s59
	s_nop 0
	global_load_lds_dwordx4 v[212:213], off
	v_lshl_add_u64 v[212:213], v[238:239], 0, s[30:31]
	s_mov_b32 m0, s60
	s_nop 0
	global_load_lds_dwordx4 v[212:213], off
	s_waitcnt vmcnt(8)
	s_waitcnt lgkmcnt(0)
	s_barrier
	s_setprio 1
	s_waitcnt lgkmcnt(0)
	v_mfma_f32_16x16x32_bf16 v[94:97], v[130:133], v[166:169], v[94:97]
	v_mfma_f32_16x16x32_bf16 v[94:97], v[134:137], v[170:173], v[94:97]
	v_mfma_f32_16x16x32_bf16 v[62:65], v[130:133], v[184:187], v[62:65]
	v_mfma_f32_16x16x32_bf16 v[62:65], v[134:137], v[188:191], v[62:65]
	v_mfma_f32_16x16x32_bf16 v[46:49], v[130:133], v[192:195], v[46:49]
	v_mfma_f32_16x16x32_bf16 v[46:49], v[134:137], v[196:199], v[46:49]
	v_mfma_f32_16x16x32_bf16 v[22:25], v[130:133], v[200:203], v[22:25]
	v_mfma_f32_16x16x32_bf16 v[22:25], v[134:137], v[232:235], v[22:25]
	v_mfma_f32_16x16x32_bf16 v[2:5], v[138:141], v[200:203], v[2:5]
	v_mfma_f32_16x16x32_bf16 v[2:5], v[142:145], v[232:235], v[2:5]
	v_mfma_f32_16x16x32_bf16 v[10:13], v[138:141], v[192:195], v[10:13]
	v_mfma_f32_16x16x32_bf16 v[10:13], v[142:145], v[196:199], v[10:13]
	v_mfma_f32_16x16x32_bf16 v[30:33], v[138:141], v[184:187], v[30:33]
	v_mfma_f32_16x16x32_bf16 v[30:33], v[142:145], v[188:191], v[30:33]
	v_mfma_f32_16x16x32_bf16 v[50:53], v[138:141], v[166:169], v[50:53]
	v_mfma_f32_16x16x32_bf16 v[50:53], v[142:145], v[170:173], v[50:53]
	v_mfma_f32_16x16x32_bf16 v[78:81], v[146:149], v[166:169], v[78:81]
	v_mfma_f32_16x16x32_bf16 v[78:81], v[150:153], v[170:173], v[78:81]
	v_mfma_f32_16x16x32_bf16 v[54:57], v[146:149], v[184:187], v[54:57]
	v_mfma_f32_16x16x32_bf16 v[54:57], v[150:153], v[188:191], v[54:57]
	v_mfma_f32_16x16x32_bf16 v[26:29], v[146:149], v[192:195], v[26:29]
	v_mfma_f32_16x16x32_bf16 v[26:29], v[150:153], v[196:199], v[26:29]
	v_mfma_f32_16x16x32_bf16 v[18:21], v[146:149], v[200:203], v[18:21]
	v_mfma_f32_16x16x32_bf16 v[18:21], v[150:153], v[232:235], v[18:21]
	v_mfma_f32_16x16x32_bf16 v[6:9], v[154:157], v[200:203], v[6:9]
	v_mfma_f32_16x16x32_bf16 v[6:9], v[162:165], v[232:235], v[6:9]
	v_mfma_f32_16x16x32_bf16 v[14:17], v[154:157], v[192:195], v[14:17]
	v_mfma_f32_16x16x32_bf16 v[14:17], v[162:165], v[196:199], v[14:17]
	v_mfma_f32_16x16x32_bf16 v[34:37], v[154:157], v[184:187], v[34:37]
	v_mfma_f32_16x16x32_bf16 v[34:37], v[162:165], v[188:191], v[34:37]
	v_mfma_f32_16x16x32_bf16 v[58:61], v[154:157], v[166:169], v[58:61]
	v_mfma_f32_16x16x32_bf16 v[58:61], v[162:165], v[170:173], v[58:61]
	s_setprio 0
	s_barrier
	s_add_i32 s25, s25, 2
	s_add_u32 s16, s16, 0x100
	s_addc_u32 s17, s17, 0
	s_add_u32 s21, s21, 0x100
	s_addc_u32 s24, s24, 0
	s_cmp_gt_u32 s25, 29
	s_cbranch_scc0 .LBB0_1997
	v_readlane_b32 s16, v253, 2
	v_readlane_b32 s17, v253, 3
	s_and_b64 vcc, exec, s[16:17]
	s_cbranch_vccz .LBB0_2000
	s_barrier

.LBB0_2111:
	s_add_u32 s16, s14, 0xfffc0080
	s_addc_u32 s17, s15, -1
	s_add_i32 s51, 0, 0x10000
	s_cmp_eq_u32 s50, 12
	s_cselect_b32 s21, s9, s17
	s_cselect_b32 s20, s46, s16
	s_cselect_b32 s17, s5, s49
	s_cselect_b32 s16, s47, s48
	s_add_i32 s54, 0, 0x14000
	v_add_u32_e32 v154, s51, v181
	v_add_u32_e32 v170, s54, v181
	ds_read_b128 v[130:133], v154
	ds_read_b128 v[134:137], v154 offset:1024
	ds_read_b128 v[150:153], v154 offset:2048
	ds_read_b128 v[154:157], v154 offset:3072
	ds_read_b128 v[158:161], v170
	ds_read_b128 v[162:165], v170 offset:1024
	ds_read_b128 v[166:169], v170 offset:2048
	ds_read_b128 v[170:173], v170 offset:3072
	s_add_i32 m0, s26, 0xc000
	ds_read_b128 v[174:177], v184
	ds_read_b128 v[186:189], v184 offset:1024
	ds_read_b128 v[190:193], v184 offset:2048
	ds_read_b128 v[194:197], v184 offset:3072
	ds_read_b128 v[198:201], v184 offset:4096
	ds_read_b128 v[202:205], v184 offset:5120
	ds_read_b128 v[206:209], v184 offset:6144
	ds_read_b128 v[210:213], v184 offset:7168
	global_load_lds_dwordx4 v146, s[14:15]
	s_add_i32 m0, s26, 0xe000
	s_nop 0
	global_load_lds_dwordx4 v148, s[14:15]
	s_waitcnt vmcnt(8)
	s_waitcnt lgkmcnt(0)
	s_barrier
	s_setprio 1
	s_waitcnt lgkmcnt(0)
	v_mfma_i32_16x16x64_i8 v[126:129], v[130:133], v[174:177], v[126:129]
	v_mfma_i32_16x16x64_i8 v[126:129], v[134:137], v[186:189], v[126:129]
	v_mfma_i32_16x16x64_i8 v[110:113], v[130:133], v[190:193], v[110:113]
	v_mfma_i32_16x16x64_i8 v[110:113], v[134:137], v[194:197], v[110:113]
	v_mfma_i32_16x16x64_i8 v[94:97], v[130:133], v[198:201], v[94:97]
	v_mfma_i32_16x16x64_i8 v[94:97], v[134:137], v[202:205], v[94:97]
	v_mfma_i32_16x16x64_i8 v[78:81], v[130:133], v[206:209], v[78:81]
	v_mfma_i32_16x16x64_i8 v[78:81], v[134:137], v[210:213], v[78:81]
	v_mfma_i32_16x16x64_i8 v[70:73], v[150:153], v[206:209], v[70:73]
	v_mfma_i32_16x16x64_i8 v[70:73], v[154:157], v[210:213], v[70:73]
	v_mfma_i32_16x16x64_i8 v[86:89], v[150:153], v[198:201], v[86:89]
	v_mfma_i32_16x16x64_i8 v[86:89], v[154:157], v[202:205], v[86:89]
	v_mfma_i32_16x16x64_i8 v[102:105], v[150:153], v[190:193], v[102:105]
	v_mfma_i32_16x16x64_i8 v[102:105], v[154:157], v[194:197], v[102:105]
	v_mfma_i32_16x16x64_i8 v[122:125], v[150:153], v[174:177], v[122:125]
	v_mfma_i32_16x16x64_i8 v[122:125], v[154:157], v[186:189], v[122:125]
	v_mfma_i32_16x16x64_i8 v[118:121], v[158:161], v[174:177], v[118:121]
	v_mfma_i32_16x16x64_i8 v[118:121], v[162:165], v[186:189], v[118:121]
	v_mfma_i32_16x16x64_i8 v[106:109], v[158:161], v[190:193], v[106:109]
	v_mfma_i32_16x16x64_i8 v[106:109], v[162:165], v[194:197], v[106:109]
	v_mfma_i32_16x16x64_i8 v[90:93], v[158:161], v[198:201], v[90:93]
	v_mfma_i32_16x16x64_i8 v[90:93], v[162:165], v[202:205], v[90:93]
	v_mfma_i32_16x16x64_i8 v[74:77], v[158:161], v[206:209], v[74:77]
	v_mfma_i32_16x16x64_i8 v[74:77], v[162:165], v[210:213], v[74:77]
	v_mfma_i32_16x16x64_i8 v[66:69], v[166:169], v[206:209], v[66:69]
	v_mfma_i32_16x16x64_i8 v[66:69], v[170:173], v[210:213], v[66:69]
	v_mfma_i32_16x16x64_i8 v[82:85], v[166:169], v[198:201], v[82:85]
	v_mfma_i32_16x16x64_i8 v[82:85], v[170:173], v[202:205], v[82:85]
	v_mfma_i32_16x16x64_i8 v[98:101], v[166:169], v[190:193], v[98:101]
	v_mfma_i32_16x16x64_i8 v[98:101], v[170:173], v[194:197], v[98:101]
	v_mfma_i32_16x16x64_i8 v[114:117], v[166:169], v[174:177], v[114:117]
	v_mfma_i32_16x16x64_i8 v[114:117], v[170:173], v[186:189], v[114:117]
	s_setprio 0
	s_barrier
	s_add_i32 s51, s51, s33
	v_lshl_add_u64 v[178:179], s[16:17], 0, v[0:1]
	s_mov_b32 m0, s51
	ds_read_b128 v[174:177], v184 offset:16384
	ds_read_b128 v[186:189], v184 offset:17408
	ds_read_b128 v[190:193], v184 offset:18432
	ds_read_b128 v[194:197], v184 offset:19456
	ds_read_b128 v[198:201], v184 offset:20480
	ds_read_b128 v[202:205], v184 offset:21504
	ds_read_b128 v[206:209], v184 offset:22528
	ds_read_b128 v[210:213], v184 offset:23552
	global_load_lds_dwordx4 v[178:179], off
	s_add_i32 m0, s51, 0x2000
	s_add_u32 s52, s16, 0x40000
	v_lshl_add_u64 v[220:221], s[16:17], 0, v[138:139]
	s_addc_u32 s53, s17, 0
	s_add_i32 s51, s54, s33
	global_load_lds_dwordx4 v[220:221], off
	s_mov_b32 m0, s51
	v_lshl_add_u64 v[226:227], s[20:21], 0, v[140:141]
	global_load_lds_dwordx4 v0, s[52:53]
	s_add_i32 m0, s51, 0x2000
	s_nop 0
	global_load_lds_dwordx4 v138, s[52:53]
	v_lshl_add_u64 v[224:225], s[20:21], 0, v[142:143]
	s_mov_b32 m0, s26
	s_nop 0
	global_load_lds_dwordx4 v[224:225], off
	s_mov_b32 m0, s27
	s_nop 0
	global_load_lds_dwordx4 v[226:227], off
	s_waitcnt vmcnt(8)
	s_waitcnt lgkmcnt(0)
	s_barrier
	s_setprio 1
	s_waitcnt lgkmcnt(0)
	v_mfma_i32_16x16x64_i8 v[62:65], v[130:133], v[174:177], v[62:65]
	v_mfma_i32_16x16x64_i8 v[62:65], v[134:137], v[186:189], v[62:65]
	v_mfma_i32_16x16x64_i8 v[46:49], v[130:133], v[190:193], v[46:49]
	v_mfma_i32_16x16x64_i8 v[46:49], v[134:137], v[194:197], v[46:49]
	v_mfma_i32_16x16x64_i8 v[30:33], v[130:133], v[198:201], v[30:33]
	v_mfma_i32_16x16x64_i8 v[30:33], v[134:137], v[202:205], v[30:33]
	v_mfma_i32_16x16x64_i8 v[14:17], v[130:133], v[206:209], v[14:17]
	v_mfma_i32_16x16x64_i8 v[14:17], v[134:137], v[210:213], v[14:17]
	v_mfma_i32_16x16x64_i8 v[6:9], v[150:153], v[206:209], v[6:9]
	v_mfma_i32_16x16x64_i8 v[6:9], v[154:157], v[210:213], v[6:9]
	v_mfma_i32_16x16x64_i8 v[22:25], v[150:153], v[198:201], v[22:25]
	v_mfma_i32_16x16x64_i8 v[22:25], v[154:157], v[202:205], v[22:25]
	v_mfma_i32_16x16x64_i8 v[38:41], v[150:153], v[190:193], v[38:41]
	v_mfma_i32_16x16x64_i8 v[38:41], v[154:157], v[194:197], v[38:41]
	v_mfma_i32_16x16x64_i8 v[54:57], v[150:153], v[174:177], v[54:57]
	v_mfma_i32_16x16x64_i8 v[54:57], v[154:157], v[186:189], v[54:57]
	v_mfma_i32_16x16x64_i8 v[58:61], v[158:161], v[174:177], v[58:61]
	v_mfma_i32_16x16x64_i8 v[58:61], v[162:165], v[186:189], v[58:61]
	v_mfma_i32_16x16x64_i8 v[42:45], v[158:161], v[190:193], v[42:45]
	v_mfma_i32_16x16x64_i8 v[42:45], v[162:165], v[194:197], v[42:45]
	v_mfma_i32_16x16x64_i8 v[26:29], v[158:161], v[198:201], v[26:29]
	v_mfma_i32_16x16x64_i8 v[26:29], v[162:165], v[202:205], v[26:29]
	v_mfma_i32_16x16x64_i8 v[10:13], v[158:161], v[206:209], v[10:13]
	v_mfma_i32_16x16x64_i8 v[10:13], v[162:165], v[210:213], v[10:13]
	v_mfma_i32_16x16x64_i8 v[2:5], v[166:169], v[206:209], v[2:5]
	v_mfma_i32_16x16x64_i8 v[2:5], v[170:173], v[210:213], v[2:5]
	v_mfma_i32_16x16x64_i8 v[18:21], v[166:169], v[198:201], v[18:21]
	v_mfma_i32_16x16x64_i8 v[18:21], v[170:173], v[202:205], v[18:21]
	v_mfma_i32_16x16x64_i8 v[34:37], v[166:169], v[190:193], v[34:37]
	v_mfma_i32_16x16x64_i8 v[34:37], v[170:173], v[194:197], v[34:37]
	v_mfma_i32_16x16x64_i8 v[50:53], v[166:169], v[174:177], v[50:53]
	v_mfma_i32_16x16x64_i8 v[50:53], v[170:173], v[186:189], v[50:53]
	s_setprio 0
	s_barrier
	s_add_i32 s51, 0, 0x18000
	s_add_i32 s52, 0, 0x1c000
	v_add_u32_e32 v154, s51, v181
	v_add_u32_e32 v170, s52, v181
	ds_read_b128 v[130:133], v154
	ds_read_b128 v[134:137], v154 offset:1024
	ds_read_b128 v[150:153], v154 offset:2048
	ds_read_b128 v[154:157], v154 offset:3072
	ds_read_b128 v[158:161], v170
	ds_read_b128 v[162:165], v170 offset:1024
	ds_read_b128 v[166:169], v170 offset:2048
	ds_read_b128 v[170:173], v170 offset:3072
	s_add_u32 s20, s20, 0x40000
	s_addc_u32 s21, s21, 0
	s_mov_b32 m0, s28
	ds_read_b128 v[174:177], v184 offset:32768
	ds_read_b128 v[186:189], v184 offset:33792
	ds_read_b128 v[190:193], v184 offset:34816
	ds_read_b128 v[194:197], v184 offset:35840
	ds_read_b128 v[198:201], v184 offset:36864
	ds_read_b128 v[202:205], v184 offset:37888
	ds_read_b128 v[206:209], v184 offset:38912
	ds_read_b128 v[210:213], v184 offset:39936
	global_load_lds_dwordx4 v142, s[20:21]
	s_mov_b32 m0, s29
	s_nop 0
	global_load_lds_dwordx4 v140, s[20:21]
	s_waitcnt vmcnt(8)
	s_waitcnt lgkmcnt(0)
	s_barrier
	s_setprio 1
	s_waitcnt lgkmcnt(0)
	v_mfma_i32_16x16x64_i8 v[126:129], v[130:133], v[174:177], v[126:129]
	v_mfma_i32_16x16x64_i8 v[126:129], v[134:137], v[186:189], v[126:129]
	v_mfma_i32_16x16x64_i8 v[110:113], v[130:133], v[190:193], v[110:113]
	v_mfma_i32_16x16x64_i8 v[110:113], v[134:137], v[194:197], v[110:113]
	v_mfma_i32_16x16x64_i8 v[94:97], v[130:133], v[198:201], v[94:97]
	v_mfma_i32_16x16x64_i8 v[94:97], v[134:137], v[202:205], v[94:97]
	v_mfma_i32_16x16x64_i8 v[78:81], v[130:133], v[206:209], v[78:81]
	v_mfma_i32_16x16x64_i8 v[78:81], v[134:137], v[210:213], v[78:81]
	v_mfma_i32_16x16x64_i8 v[70:73], v[150:153], v[206:209], v[70:73]
	v_mfma_i32_16x16x64_i8 v[70:73], v[154:157], v[210:213], v[70:73]
	v_mfma_i32_16x16x64_i8 v[86:89], v[150:153], v[198:201], v[86:89]
	v_mfma_i32_16x16x64_i8 v[86:89], v[154:157], v[202:205], v[86:89]
	v_mfma_i32_16x16x64_i8 v[102:105], v[150:153], v[190:193], v[102:105]
	v_mfma_i32_16x16x64_i8 v[102:105], v[154:157], v[194:197], v[102:105]
	v_mfma_i32_16x16x64_i8 v[122:125], v[150:153], v[174:177], v[122:125]
	v_mfma_i32_16x16x64_i8 v[122:125], v[154:157], v[186:189], v[122:125]
	v_mfma_i32_16x16x64_i8 v[118:121], v[158:161], v[174:177], v[118:121]
	v_mfma_i32_16x16x64_i8 v[118:121], v[162:165], v[186:189], v[118:121]
	v_mfma_i32_16x16x64_i8 v[106:109], v[158:161], v[190:193], v[106:109]
	v_mfma_i32_16x16x64_i8 v[106:109], v[162:165], v[194:197], v[106:109]
	v_mfma_i32_16x16x64_i8 v[90:93], v[158:161], v[198:201], v[90:93]
	v_mfma_i32_16x16x64_i8 v[90:93], v[162:165], v[202:205], v[90:93]
	v_mfma_i32_16x16x64_i8 v[74:77], v[158:161], v[206:209], v[74:77]
	v_mfma_i32_16x16x64_i8 v[74:77], v[162:165], v[210:213], v[74:77]
	v_mfma_i32_16x16x64_i8 v[66:69], v[166:169], v[206:209], v[66:69]
	v_mfma_i32_16x16x64_i8 v[66:69], v[170:173], v[210:213], v[66:69]
	v_mfma_i32_16x16x64_i8 v[82:85], v[166:169], v[198:201], v[82:85]
	v_mfma_i32_16x16x64_i8 v[82:85], v[170:173], v[202:205], v[82:85]
	v_mfma_i32_16x16x64_i8 v[98:101], v[166:169], v[190:193], v[98:101]
	v_mfma_i32_16x16x64_i8 v[98:101], v[170:173], v[194:197], v[98:101]
	v_mfma_i32_16x16x64_i8 v[114:117], v[166:169], v[174:177], v[114:117]
	v_mfma_i32_16x16x64_i8 v[114:117], v[170:173], v[186:189], v[114:117]
	s_setprio 0
	s_barrier
	s_add_i32 s20, s51, s33
	v_lshl_add_u64 v[178:179], v[178:179], 0, s[30:31]
	s_mov_b32 m0, s20
	ds_read_b128 v[174:177], v184 offset:49152
	ds_read_b128 v[186:189], v184 offset:50176
	ds_read_b128 v[190:193], v184 offset:51200
	ds_read_b128 v[194:197], v184 offset:52224
	ds_read_b128 v[198:201], v184 offset:53248
	ds_read_b128 v[202:205], v184 offset:54272
	ds_read_b128 v[206:209], v184 offset:55296
	ds_read_b128 v[210:213], v184 offset:56320
	global_load_lds_dwordx4 v[178:179], off
	s_add_i32 m0, s20, 0x2000
	s_add_u32 s16, s16, 0x40080
	v_lshl_add_u64 v[178:179], v[220:221], 0, s[30:31]
	s_addc_u32 s17, s17, 0
	s_add_i32 s20, s52, s33
	global_load_lds_dwordx4 v[178:179], off
	s_mov_b32 m0, s20
	s_nop 0
	global_load_lds_dwordx4 v0, s[16:17]
	s_add_i32 m0, s20, 0x2000
	s_nop 0
	global_load_lds_dwordx4 v138, s[16:17]
	v_lshl_add_u64 v[178:179], v[224:225], 0, s[30:31]
	s_mov_b32 m0, s34
	s_nop 0
	global_load_lds_dwordx4 v[178:179], off
	v_lshl_add_u64 v[178:179], v[226:227], 0, s[30:31]
	s_mov_b32 m0, s35
	s_nop 0
	global_load_lds_dwordx4 v[178:179], off
	s_waitcnt vmcnt(8)
	s_waitcnt lgkmcnt(0)
	s_barrier
	s_setprio 1
	s_waitcnt lgkmcnt(0)
	v_mfma_i32_16x16x64_i8 v[62:65], v[130:133], v[174:177], v[62:65]
	v_mfma_i32_16x16x64_i8 v[62:65], v[134:137], v[186:189], v[62:65]
	v_mfma_i32_16x16x64_i8 v[46:49], v[130:133], v[190:193], v[46:49]
	v_mfma_i32_16x16x64_i8 v[46:49], v[134:137], v[194:197], v[46:49]
	v_mfma_i32_16x16x64_i8 v[30:33], v[130:133], v[198:201], v[30:33]
	v_mfma_i32_16x16x64_i8 v[30:33], v[134:137], v[202:205], v[30:33]
	v_mfma_i32_16x16x64_i8 v[14:17], v[130:133], v[206:209], v[14:17]
	v_mfma_i32_16x16x64_i8 v[14:17], v[134:137], v[210:213], v[14:17]
	v_mfma_i32_16x16x64_i8 v[6:9], v[150:153], v[206:209], v[6:9]
	v_mfma_i32_16x16x64_i8 v[6:9], v[154:157], v[210:213], v[6:9]
	v_mfma_i32_16x16x64_i8 v[22:25], v[150:153], v[198:201], v[22:25]
	v_mfma_i32_16x16x64_i8 v[22:25], v[154:157], v[202:205], v[22:25]
	v_mfma_i32_16x16x64_i8 v[38:41], v[150:153], v[190:193], v[38:41]
	v_mfma_i32_16x16x64_i8 v[38:41], v[154:157], v[194:197], v[38:41]
	v_mfma_i32_16x16x64_i8 v[54:57], v[150:153], v[174:177], v[54:57]
	v_mfma_i32_16x16x64_i8 v[54:57], v[154:157], v[186:189], v[54:57]
	v_mfma_i32_16x16x64_i8 v[58:61], v[158:161], v[174:177], v[58:61]
	v_mfma_i32_16x16x64_i8 v[58:61], v[162:165], v[186:189], v[58:61]
	v_mfma_i32_16x16x64_i8 v[42:45], v[158:161], v[190:193], v[42:45]
	v_mfma_i32_16x16x64_i8 v[42:45], v[162:165], v[194:197], v[42:45]
	v_mfma_i32_16x16x64_i8 v[26:29], v[158:161], v[198:201], v[26:29]
	v_mfma_i32_16x16x64_i8 v[26:29], v[162:165], v[202:205], v[26:29]
	v_mfma_i32_16x16x64_i8 v[10:13], v[158:161], v[206:209], v[10:13]
	v_mfma_i32_16x16x64_i8 v[10:13], v[162:165], v[210:213], v[10:13]
	v_mfma_i32_16x16x64_i8 v[2:5], v[166:169], v[206:209], v[2:5]
	v_mfma_i32_16x16x64_i8 v[2:5], v[170:173], v[210:213], v[2:5]
	v_mfma_i32_16x16x64_i8 v[18:21], v[166:169], v[198:201], v[18:21]
	v_mfma_i32_16x16x64_i8 v[18:21], v[170:173], v[202:205], v[18:21]
	v_mfma_i32_16x16x64_i8 v[34:37], v[166:169], v[190:193], v[34:37]
	v_mfma_i32_16x16x64_i8 v[34:37], v[170:173], v[194:197], v[34:37]
	v_mfma_i32_16x16x64_i8 v[50:53], v[166:169], v[174:177], v[50:53]
	v_mfma_i32_16x16x64_i8 v[50:53], v[170:173], v[186:189], v[50:53]
	s_setprio 0
	s_barrier
	s_add_i32 s50, s50, 2
	s_add_u32 s14, s14, 0x100
	s_addc_u32 s15, s15, 0
	s_add_u32 s48, s48, 0x100
	s_addc_u32 s49, s49, 0
	s_cmp_gt_u32 s50, 13
	s_cbranch_scc0 .LBB0_2111
	v_readlane_b32 s14, v253, 2
	v_readlane_b32 s15, v253, 3
	s_and_b64 vcc, exec, s[14:15]
	s_cbranch_vccz .LBB0_2114
	s_barrier

.LBB0_2193:
	s_add_u32 s16, s12, 0x100
	s_addc_u32 s17, s13, 0
	s_add_i32 s67, 0, 0x10000
	s_cmpk_eq_i32 s19, 0x54
	s_cselect_b32 s23, s7, s17
	s_cselect_b32 s22, s6, s16
	s_cselect_b32 s21, s11, s18
	s_cselect_b32 s20, s10, s15
	s_add_i32 s68, 0, 0x14000
	v_add_u32_e32 v142, s67, v205
	v_add_u32_e32 v162, s68, v205
	ds_read_b128 v[130:133], v142
	ds_read_b128 v[134:137], v142 offset:1024
	ds_read_b128 v[138:141], v142 offset:2048
	ds_read_b128 v[142:145], v142 offset:3072
	ds_read_b128 v[146:149], v162
	ds_read_b128 v[150:153], v162 offset:1024
	ds_read_b128 v[154:157], v162 offset:2048
	ds_read_b128 v[162:165], v162 offset:3072
	s_add_i32 m0, s28, 0xc000
	ds_read_b128 v[166:169], v230
	ds_read_b128 v[170:173], v230 offset:1024
	ds_read_b128 v[184:187], v230 offset:2048
	ds_read_b128 v[188:191], v230 offset:3072
	ds_read_b128 v[192:195], v230 offset:4096
	ds_read_b128 v[196:199], v230 offset:5120
	ds_read_b128 v[200:203], v230 offset:6144
	ds_read_b128 v[232:235], v230 offset:7168
	global_load_lds_dwordx4 v180, s[12:13]
	s_add_i32 m0, s28, 0xe000
	s_nop 0
	global_load_lds_dwordx4 v182, s[12:13]
	s_waitcnt vmcnt(8)
	s_waitcnt lgkmcnt(0)
	s_barrier
	s_setprio 1
	s_waitcnt lgkmcnt(0)
	v_mfma_f32_16x16x32_bf16 v[126:129], v[130:133], v[166:169], v[126:129]
	v_mfma_f32_16x16x32_bf16 v[126:129], v[134:137], v[170:173], v[126:129]
	v_mfma_f32_16x16x32_bf16 v[118:121], v[130:133], v[184:187], v[118:121]
	v_mfma_f32_16x16x32_bf16 v[118:121], v[134:137], v[188:191], v[118:121]
	v_mfma_f32_16x16x32_bf16 v[110:113], v[130:133], v[192:195], v[110:113]
	v_mfma_f32_16x16x32_bf16 v[110:113], v[134:137], v[196:199], v[110:113]
	v_mfma_f32_16x16x32_bf16 v[102:105], v[130:133], v[200:203], v[102:105]
	v_mfma_f32_16x16x32_bf16 v[102:105], v[134:137], v[232:235], v[102:105]
	v_mfma_f32_16x16x32_bf16 v[38:41], v[138:141], v[200:203], v[38:41]
	v_mfma_f32_16x16x32_bf16 v[38:41], v[142:145], v[232:235], v[38:41]
	v_mfma_f32_16x16x32_bf16 v[66:69], v[138:141], v[192:195], v[66:69]
	v_mfma_f32_16x16x32_bf16 v[66:69], v[142:145], v[196:199], v[66:69]
	v_mfma_f32_16x16x32_bf16 v[86:89], v[138:141], v[184:187], v[86:89]
	v_mfma_f32_16x16x32_bf16 v[86:89], v[142:145], v[188:191], v[86:89]
	v_mfma_f32_16x16x32_bf16 v[74:77], v[138:141], v[166:169], v[74:77]
	v_mfma_f32_16x16x32_bf16 v[74:77], v[142:145], v[170:173], v[74:77]
	v_mfma_f32_16x16x32_bf16 v[122:125], v[146:149], v[166:169], v[122:125]
	v_mfma_f32_16x16x32_bf16 v[122:125], v[150:153], v[170:173], v[122:125]
	v_mfma_f32_16x16x32_bf16 v[114:117], v[146:149], v[184:187], v[114:117]
	v_mfma_f32_16x16x32_bf16 v[114:117], v[150:153], v[188:191], v[114:117]
	v_mfma_f32_16x16x32_bf16 v[106:109], v[146:149], v[192:195], v[106:109]
	v_mfma_f32_16x16x32_bf16 v[106:109], v[150:153], v[196:199], v[106:109]
	v_mfma_f32_16x16x32_bf16 v[98:101], v[146:149], v[200:203], v[98:101]
	v_mfma_f32_16x16x32_bf16 v[98:101], v[150:153], v[232:235], v[98:101]
	v_mfma_f32_16x16x32_bf16 v[42:45], v[154:157], v[200:203], v[42:45]
	v_mfma_f32_16x16x32_bf16 v[42:45], v[162:165], v[232:235], v[42:45]
	v_mfma_f32_16x16x32_bf16 v[70:73], v[154:157], v[192:195], v[70:73]
	v_mfma_f32_16x16x32_bf16 v[70:73], v[162:165], v[196:199], v[70:73]
	v_mfma_f32_16x16x32_bf16 v[90:93], v[154:157], v[184:187], v[90:93]
	v_mfma_f32_16x16x32_bf16 v[90:93], v[162:165], v[188:191], v[90:93]
	v_mfma_f32_16x16x32_bf16 v[82:85], v[154:157], v[166:169], v[82:85]
	v_mfma_f32_16x16x32_bf16 v[82:85], v[162:165], v[170:173], v[82:85]
	s_setprio 0
	s_barrier
	s_add_i32 s12, s67, s33
	v_lshl_add_u64 v[212:213], s[20:21], 0, v[0:1]
	s_mov_b32 m0, s12
	ds_read_b128 v[166:169], v230 offset:16384
	ds_read_b128 v[170:173], v230 offset:17408
	ds_read_b128 v[184:187], v230 offset:18432
	ds_read_b128 v[188:191], v230 offset:19456
	ds_read_b128 v[192:195], v230 offset:20480
	ds_read_b128 v[196:199], v230 offset:21504
	ds_read_b128 v[200:203], v230 offset:22528
	ds_read_b128 v[232:235], v230 offset:23552
	global_load_lds_dwordx4 v[212:213], off
	s_add_i32 m0, s12, 0x2000
	s_add_u32 s12, s20, 0x160000
	v_lshl_add_u64 v[220:221], s[20:21], 0, v[158:159]
	s_addc_u32 s13, s21, 0
	s_add_i32 s67, s68, s33
	global_load_lds_dwordx4 v[220:221], off
	s_mov_b32 m0, s67
	v_lshl_add_u64 v[238:239], s[22:23], 0, v[160:161]
	global_load_lds_dwordx4 v0, s[12:13]
	s_add_i32 m0, s67, 0x2000
	s_nop 0
	global_load_lds_dwordx4 v158, s[12:13]
	v_lshl_add_u64 v[236:237], s[22:23], 0, v[174:175]
	s_mov_b32 m0, s28
	s_nop 0
	global_load_lds_dwordx4 v[236:237], off
	s_mov_b32 m0, s29
	s_nop 0
	global_load_lds_dwordx4 v[238:239], off
	s_waitcnt vmcnt(8)
	s_waitcnt lgkmcnt(0)
	s_barrier
	s_setprio 1
	s_waitcnt lgkmcnt(0)
	v_mfma_f32_16x16x32_bf16 v[94:97], v[130:133], v[166:169], v[94:97]
	v_mfma_f32_16x16x32_bf16 v[94:97], v[134:137], v[170:173], v[94:97]
	v_mfma_f32_16x16x32_bf16 v[62:65], v[130:133], v[184:187], v[62:65]
	v_mfma_f32_16x16x32_bf16 v[62:65], v[134:137], v[188:191], v[62:65]
	v_mfma_f32_16x16x32_bf16 v[46:49], v[130:133], v[192:195], v[46:49]
	v_mfma_f32_16x16x32_bf16 v[46:49], v[134:137], v[196:199], v[46:49]
	v_mfma_f32_16x16x32_bf16 v[22:25], v[130:133], v[200:203], v[22:25]
	v_mfma_f32_16x16x32_bf16 v[22:25], v[134:137], v[232:235], v[22:25]
	v_mfma_f32_16x16x32_bf16 v[2:5], v[138:141], v[200:203], v[2:5]
	v_mfma_f32_16x16x32_bf16 v[2:5], v[142:145], v[232:235], v[2:5]
	v_mfma_f32_16x16x32_bf16 v[10:13], v[138:141], v[192:195], v[10:13]
	v_mfma_f32_16x16x32_bf16 v[10:13], v[142:145], v[196:199], v[10:13]
	v_mfma_f32_16x16x32_bf16 v[30:33], v[138:141], v[184:187], v[30:33]
	v_mfma_f32_16x16x32_bf16 v[30:33], v[142:145], v[188:191], v[30:33]
	v_mfma_f32_16x16x32_bf16 v[50:53], v[138:141], v[166:169], v[50:53]
	v_mfma_f32_16x16x32_bf16 v[50:53], v[142:145], v[170:173], v[50:53]
	v_mfma_f32_16x16x32_bf16 v[78:81], v[146:149], v[166:169], v[78:81]
	v_mfma_f32_16x16x32_bf16 v[78:81], v[150:153], v[170:173], v[78:81]
	v_mfma_f32_16x16x32_bf16 v[54:57], v[146:149], v[184:187], v[54:57]
	v_mfma_f32_16x16x32_bf16 v[54:57], v[150:153], v[188:191], v[54:57]
	v_mfma_f32_16x16x32_bf16 v[26:29], v[146:149], v[192:195], v[26:29]
	v_mfma_f32_16x16x32_bf16 v[26:29], v[150:153], v[196:199], v[26:29]
	v_mfma_f32_16x16x32_bf16 v[18:21], v[146:149], v[200:203], v[18:21]
	v_mfma_f32_16x16x32_bf16 v[18:21], v[150:153], v[232:235], v[18:21]
	v_mfma_f32_16x16x32_bf16 v[6:9], v[154:157], v[200:203], v[6:9]
	v_mfma_f32_16x16x32_bf16 v[6:9], v[162:165], v[232:235], v[6:9]
	v_mfma_f32_16x16x32_bf16 v[14:17], v[154:157], v[192:195], v[14:17]
	v_mfma_f32_16x16x32_bf16 v[14:17], v[162:165], v[196:199], v[14:17]
	v_mfma_f32_16x16x32_bf16 v[34:37], v[154:157], v[184:187], v[34:37]
	v_mfma_f32_16x16x32_bf16 v[34:37], v[162:165], v[188:191], v[34:37]
	v_mfma_f32_16x16x32_bf16 v[58:61], v[154:157], v[166:169], v[58:61]
	v_mfma_f32_16x16x32_bf16 v[58:61], v[162:165], v[170:173], v[58:61]
	s_setprio 0
	s_barrier
	s_add_i32 s67, 0, 0x18000
	s_add_i32 s68, 0, 0x1c000
	v_add_u32_e32 v142, s67, v205
	v_add_u32_e32 v162, s68, v205
	ds_read_b128 v[130:133], v142
	ds_read_b128 v[134:137], v142 offset:1024
	ds_read_b128 v[138:141], v142 offset:2048
	ds_read_b128 v[142:145], v142 offset:3072
	ds_read_b128 v[146:149], v162
	ds_read_b128 v[150:153], v162 offset:1024
	ds_read_b128 v[154:157], v162 offset:2048
	ds_read_b128 v[162:165], v162 offset:3072
	s_add_u32 s12, s22, 0x160000
	s_addc_u32 s13, s23, 0
	s_mov_b32 m0, s34
	ds_read_b128 v[166:169], v230 offset:32768
	ds_read_b128 v[170:173], v230 offset:33792
	ds_read_b128 v[184:187], v230 offset:34816
	ds_read_b128 v[188:191], v230 offset:35840
	ds_read_b128 v[192:195], v230 offset:36864
	ds_read_b128 v[196:199], v230 offset:37888
	ds_read_b128 v[200:203], v230 offset:38912
	ds_read_b128 v[232:235], v230 offset:39936
	global_load_lds_dwordx4 v174, s[12:13]
	s_mov_b32 m0, s35
	s_nop 0
	global_load_lds_dwordx4 v160, s[12:13]
	s_waitcnt vmcnt(8)
	s_waitcnt lgkmcnt(0)
	s_barrier
	s_setprio 1
	s_waitcnt lgkmcnt(0)
	v_mfma_f32_16x16x32_bf16 v[126:129], v[130:133], v[166:169], v[126:129]
	v_mfma_f32_16x16x32_bf16 v[126:129], v[134:137], v[170:173], v[126:129]
	v_mfma_f32_16x16x32_bf16 v[118:121], v[130:133], v[184:187], v[118:121]
	v_mfma_f32_16x16x32_bf16 v[118:121], v[134:137], v[188:191], v[118:121]
	v_mfma_f32_16x16x32_bf16 v[110:113], v[130:133], v[192:195], v[110:113]
	v_mfma_f32_16x16x32_bf16 v[110:113], v[134:137], v[196:199], v[110:113]
	v_mfma_f32_16x16x32_bf16 v[102:105], v[130:133], v[200:203], v[102:105]
	v_mfma_f32_16x16x32_bf16 v[102:105], v[134:137], v[232:235], v[102:105]
	v_mfma_f32_16x16x32_bf16 v[38:41], v[138:141], v[200:203], v[38:41]
	v_mfma_f32_16x16x32_bf16 v[38:41], v[142:145], v[232:235], v[38:41]
	v_mfma_f32_16x16x32_bf16 v[66:69], v[138:141], v[192:195], v[66:69]
	v_mfma_f32_16x16x32_bf16 v[66:69], v[142:145], v[196:199], v[66:69]
	v_mfma_f32_16x16x32_bf16 v[86:89], v[138:141], v[184:187], v[86:89]
	v_mfma_f32_16x16x32_bf16 v[86:89], v[142:145], v[188:191], v[86:89]
	v_mfma_f32_16x16x32_bf16 v[74:77], v[138:141], v[166:169], v[74:77]
	v_mfma_f32_16x16x32_bf16 v[74:77], v[142:145], v[170:173], v[74:77]
	v_mfma_f32_16x16x32_bf16 v[122:125], v[146:149], v[166:169], v[122:125]
	v_mfma_f32_16x16x32_bf16 v[122:125], v[150:153], v[170:173], v[122:125]
	v_mfma_f32_16x16x32_bf16 v[114:117], v[146:149], v[184:187], v[114:117]
	v_mfma_f32_16x16x32_bf16 v[114:117], v[150:153], v[188:191], v[114:117]
	v_mfma_f32_16x16x32_bf16 v[106:109], v[146:149], v[192:195], v[106:109]
	v_mfma_f32_16x16x32_bf16 v[106:109], v[150:153], v[196:199], v[106:109]
	v_mfma_f32_16x16x32_bf16 v[98:101], v[146:149], v[200:203], v[98:101]
	v_mfma_f32_16x16x32_bf16 v[98:101], v[150:153], v[232:235], v[98:101]
	v_mfma_f32_16x16x32_bf16 v[42:45], v[154:157], v[200:203], v[42:45]
	v_mfma_f32_16x16x32_bf16 v[42:45], v[162:165], v[232:235], v[42:45]
	v_mfma_f32_16x16x32_bf16 v[70:73], v[154:157], v[192:195], v[70:73]
	v_mfma_f32_16x16x32_bf16 v[70:73], v[162:165], v[196:199], v[70:73]
	v_mfma_f32_16x16x32_bf16 v[90:93], v[154:157], v[184:187], v[90:93]
	v_mfma_f32_16x16x32_bf16 v[90:93], v[162:165], v[188:191], v[90:93]
	v_mfma_f32_16x16x32_bf16 v[82:85], v[154:157], v[166:169], v[82:85]
	v_mfma_f32_16x16x32_bf16 v[82:85], v[162:165], v[170:173], v[82:85]
	s_setprio 0
	s_barrier
	s_add_i32 s12, s67, s33
	v_lshl_add_u64 v[212:213], v[212:213], 0, s[30:31]
	s_mov_b32 m0, s12
	ds_read_b128 v[166:169], v230 offset:49152
	ds_read_b128 v[170:173], v230 offset:50176
	ds_read_b128 v[184:187], v230 offset:51200
	ds_read_b128 v[188:191], v230 offset:52224
	ds_read_b128 v[192:195], v230 offset:53248
	ds_read_b128 v[196:199], v230 offset:54272
	ds_read_b128 v[200:203], v230 offset:55296
	ds_read_b128 v[232:235], v230 offset:56320
	global_load_lds_dwordx4 v[212:213], off
	s_add_i32 m0, s12, 0x2000
	s_add_u32 s12, s20, 0x160080
	v_lshl_add_u64 v[212:213], v[220:221], 0, s[30:31]
	s_addc_u32 s13, s21, 0
	s_add_i32 s20, s68, s33
	global_load_lds_dwordx4 v[212:213], off
	s_mov_b32 m0, s20
	s_nop 0
	global_load_lds_dwordx4 v0, s[12:13]
	s_add_i32 m0, s20, 0x2000
	s_nop 0
	global_load_lds_dwordx4 v158, s[12:13]
	v_lshl_add_u64 v[212:213], v[236:237], 0, s[30:31]
	s_mov_b32 m0, s55
	s_nop 0
	global_load_lds_dwordx4 v[212:213], off
	v_lshl_add_u64 v[212:213], v[238:239], 0, s[30:31]
	s_mov_b32 m0, s56
	s_nop 0
	global_load_lds_dwordx4 v[212:213], off
	s_waitcnt vmcnt(8)
	s_waitcnt lgkmcnt(0)
	s_barrier
	s_setprio 1
	s_waitcnt lgkmcnt(0)
	v_mfma_f32_16x16x32_bf16 v[94:97], v[130:133], v[166:169], v[94:97]
	v_mfma_f32_16x16x32_bf16 v[94:97], v[134:137], v[170:173], v[94:97]
	v_mfma_f32_16x16x32_bf16 v[62:65], v[130:133], v[184:187], v[62:65]
	v_mfma_f32_16x16x32_bf16 v[62:65], v[134:137], v[188:191], v[62:65]
	v_mfma_f32_16x16x32_bf16 v[46:49], v[130:133], v[192:195], v[46:49]
	v_mfma_f32_16x16x32_bf16 v[46:49], v[134:137], v[196:199], v[46:49]
	v_mfma_f32_16x16x32_bf16 v[22:25], v[130:133], v[200:203], v[22:25]
	v_mfma_f32_16x16x32_bf16 v[22:25], v[134:137], v[232:235], v[22:25]
	v_mfma_f32_16x16x32_bf16 v[2:5], v[138:141], v[200:203], v[2:5]
	v_mfma_f32_16x16x32_bf16 v[2:5], v[142:145], v[232:235], v[2:5]
	v_mfma_f32_16x16x32_bf16 v[10:13], v[138:141], v[192:195], v[10:13]
	v_mfma_f32_16x16x32_bf16 v[10:13], v[142:145], v[196:199], v[10:13]
	v_mfma_f32_16x16x32_bf16 v[30:33], v[138:141], v[184:187], v[30:33]
	v_mfma_f32_16x16x32_bf16 v[30:33], v[142:145], v[188:191], v[30:33]
	v_mfma_f32_16x16x32_bf16 v[50:53], v[138:141], v[166:169], v[50:53]
	v_mfma_f32_16x16x32_bf16 v[50:53], v[142:145], v[170:173], v[50:53]
	v_mfma_f32_16x16x32_bf16 v[78:81], v[146:149], v[166:169], v[78:81]
	v_mfma_f32_16x16x32_bf16 v[78:81], v[150:153], v[170:173], v[78:81]
	v_mfma_f32_16x16x32_bf16 v[54:57], v[146:149], v[184:187], v[54:57]
	v_mfma_f32_16x16x32_bf16 v[54:57], v[150:153], v[188:191], v[54:57]
	v_mfma_f32_16x16x32_bf16 v[26:29], v[146:149], v[192:195], v[26:29]
	v_mfma_f32_16x16x32_bf16 v[26:29], v[150:153], v[196:199], v[26:29]
	v_mfma_f32_16x16x32_bf16 v[18:21], v[146:149], v[200:203], v[18:21]
	v_mfma_f32_16x16x32_bf16 v[18:21], v[150:153], v[232:235], v[18:21]
	v_mfma_f32_16x16x32_bf16 v[6:9], v[154:157], v[200:203], v[6:9]
	v_mfma_f32_16x16x32_bf16 v[6:9], v[162:165], v[232:235], v[6:9]
	v_mfma_f32_16x16x32_bf16 v[14:17], v[154:157], v[192:195], v[14:17]
	v_mfma_f32_16x16x32_bf16 v[14:17], v[162:165], v[196:199], v[14:17]
	v_mfma_f32_16x16x32_bf16 v[34:37], v[154:157], v[184:187], v[34:37]
	v_mfma_f32_16x16x32_bf16 v[34:37], v[162:165], v[188:191], v[34:37]
	v_mfma_f32_16x16x32_bf16 v[58:61], v[154:157], v[166:169], v[58:61]
	v_mfma_f32_16x16x32_bf16 v[58:61], v[162:165], v[170:173], v[58:61]
	s_setprio 0
	s_barrier
	s_add_i32 s19, s19, 2
	s_add_u32 s15, s15, 0x100
	s_addc_u32 s18, s18, 0
	s_cmpk_gt_u32 s19, 0x55
	s_mov_b64 s[12:13], s[16:17]
	s_cbranch_scc0 .LBB0_2193
	v_readlane_b32 s12, v253, 2
	v_readlane_b32 s13, v253, 3
	s_and_b64 vcc, exec, s[12:13]
	s_cbranch_vccz .LBB0_2196
	s_barrier
